# re-measure of noprio + interleaved LDS-DMA version (unchanged file)
# baseline (speedup 1.0000x reference)
.LBB0_140:
	s_add_u32 s2, s22, 0xfff80080
	s_addc_u32 s20, s23, -1
	s_add_i32 s45, 0, 0x10000
	s_cmp_eq_u32 s44, 28
	s_cselect_b32 s25, s15, s20
	s_cselect_b32 s24, s40, s2
	v_add_u32_e32 v144, s45, v148
	s_cselect_b32 s21, s13, s43
	s_cselect_b32 s20, s41, s42
	s_add_u32 s100, s22, 0xfff80000
	s_addc_u32 s101, s23, -1
	s_add_i32 s2, 0, 0x14000
	s_mov_b32 m0, s35
	ds_read_b128 v[140:143], v144
	ds_read_b128 v[152:155], v144 offset:1024
	ds_read_b128 v[156:159], v144 offset:2048
	ds_read_b128 v[160:163], v144 offset:3072
	global_load_lds_dwordx4 v136, s[100:101]
	s_mov_b32 m0, s36
	v_add_u32_e32 v144, s2, v148
	ds_read_b128 v[164:167], v144
	ds_read_b128 v[168:171], v144 offset:1024
	ds_read_b128 v[172:175], v144 offset:2048
	ds_read_b128 v[176:179], v144 offset:3072
	global_load_lds_dwordx4 v138, s[100:101]
	s_add_i32 m0, s29, 0xc000
	ds_read_b128 v[180:183], v151
	ds_read_b128 v[184:187], v151 offset:1024
	ds_read_b128 v[188:191], v151 offset:2048
	ds_read_b128 v[192:195], v151 offset:3072
	global_load_lds_dwordx4 v136, s[22:23]
	s_add_i32 m0, s29, 0xe000
	ds_read_b128 v[206:209], v151 offset:4096
	ds_read_b128 v[210:213], v151 offset:5120
	ds_read_b128 v[214:217], v151 offset:6144
	ds_read_b128 v[218:221], v151 offset:7168
	global_load_lds_dwordx4 v138, s[22:23]
	s_waitcnt vmcnt(8)
	s_waitcnt lgkmcnt(0)
	s_barrier
	s_waitcnt lgkmcnt(0)
	v_mfma_f32_16x16x32_bf16 v[126:129], v[140:143], v[180:183], v[126:129]
	v_mfma_f32_16x16x32_bf16 v[122:125], v[156:159], v[180:183], v[122:125]
	v_mfma_f32_16x16x32_bf16 v[110:113], v[140:143], v[188:191], v[110:113]
	v_mfma_f32_16x16x32_bf16 v[106:109], v[156:159], v[188:191], v[106:109]
	v_mfma_f32_16x16x32_bf16 v[94:97], v[140:143], v[206:209], v[94:97]
	v_mfma_f32_16x16x32_bf16 v[90:93], v[156:159], v[206:209], v[90:93]
	v_mfma_f32_16x16x32_bf16 v[78:81], v[140:143], v[214:217], v[78:81]
	v_mfma_f32_16x16x32_bf16 v[74:77], v[156:159], v[214:217], v[74:77]
	v_mfma_f32_16x16x32_bf16 v[126:129], v[152:155], v[184:187], v[126:129]
	v_mfma_f32_16x16x32_bf16 v[122:125], v[160:163], v[184:187], v[122:125]
	v_mfma_f32_16x16x32_bf16 v[110:113], v[152:155], v[192:195], v[110:113]
	v_mfma_f32_16x16x32_bf16 v[106:109], v[160:163], v[192:195], v[106:109]
	v_mfma_f32_16x16x32_bf16 v[94:97], v[152:155], v[210:213], v[94:97]
	v_mfma_f32_16x16x32_bf16 v[90:93], v[160:163], v[210:213], v[90:93]
	v_mfma_f32_16x16x32_bf16 v[78:81], v[152:155], v[218:221], v[78:81]
	v_mfma_f32_16x16x32_bf16 v[74:77], v[160:163], v[218:221], v[74:77]
	v_mfma_f32_16x16x32_bf16 v[118:121], v[164:167], v[180:183], v[118:121]
	v_mfma_f32_16x16x32_bf16 v[114:117], v[172:175], v[180:183], v[114:117]
	v_mfma_f32_16x16x32_bf16 v[102:105], v[164:167], v[188:191], v[102:105]
	v_mfma_f32_16x16x32_bf16 v[98:101], v[172:175], v[188:191], v[98:101]
	v_mfma_f32_16x16x32_bf16 v[86:89], v[164:167], v[206:209], v[86:89]
	v_mfma_f32_16x16x32_bf16 v[82:85], v[172:175], v[206:209], v[82:85]
	v_mfma_f32_16x16x32_bf16 v[70:73], v[164:167], v[214:217], v[70:73]
	v_mfma_f32_16x16x32_bf16 v[66:69], v[172:175], v[214:217], v[66:69]
	v_mfma_f32_16x16x32_bf16 v[118:121], v[168:171], v[184:187], v[118:121]
	v_mfma_f32_16x16x32_bf16 v[114:117], v[176:179], v[184:187], v[114:117]
	v_mfma_f32_16x16x32_bf16 v[102:105], v[168:171], v[192:195], v[102:105]
	v_mfma_f32_16x16x32_bf16 v[98:101], v[176:179], v[192:195], v[98:101]
	v_mfma_f32_16x16x32_bf16 v[86:89], v[168:171], v[210:213], v[86:89]
	v_mfma_f32_16x16x32_bf16 v[82:85], v[176:179], v[210:213], v[82:85]
	s_barrier
	v_mfma_f32_16x16x32_bf16 v[70:73], v[168:171], v[218:221], v[70:73]
	v_mfma_f32_16x16x32_bf16 v[66:69], v[176:179], v[218:221], v[66:69]
	s_add_u32 s46, s20, 0x80000
	s_addc_u32 s47, s21, 0
	s_add_i32 s45, s45, s28
	s_mov_b32 m0, s45
	ds_read_b128 v[180:183], v151 offset:16384
	ds_read_b128 v[184:187], v151 offset:17408
	global_load_lds_dwordx4 v0, s[20:21]
	s_add_i32 m0, s45, 0x2000
	s_add_i32 s2, s2, s28
	ds_read_b128 v[188:191], v151 offset:18432
	ds_read_b128 v[192:195], v151 offset:19456
	global_load_lds_dwordx4 v130, s[20:21]
	s_mov_b32 m0, s2
	ds_read_b128 v[206:209], v151 offset:20480
	ds_read_b128 v[210:213], v151 offset:21504
	global_load_lds_dwordx4 v0, s[46:47]
	s_add_i32 m0, s2, 0x2000
	ds_read_b128 v[214:217], v151 offset:22528
	ds_read_b128 v[218:221], v151 offset:23552
	global_load_lds_dwordx4 v130, s[46:47]
	s_waitcnt vmcnt(6)
	s_waitcnt lgkmcnt(0)
	s_barrier
	s_waitcnt lgkmcnt(0)
	v_mfma_f32_16x16x32_bf16 v[62:65], v[140:143], v[180:183], v[62:65]
	v_mfma_f32_16x16x32_bf16 v[58:61], v[156:159], v[180:183], v[58:61]
	v_mfma_f32_16x16x32_bf16 v[46:49], v[140:143], v[188:191], v[46:49]
	v_mfma_f32_16x16x32_bf16 v[42:45], v[156:159], v[188:191], v[42:45]
	v_mfma_f32_16x16x32_bf16 v[30:33], v[140:143], v[206:209], v[30:33]
	v_mfma_f32_16x16x32_bf16 v[26:29], v[156:159], v[206:209], v[26:29]
	v_mfma_f32_16x16x32_bf16 v[14:17], v[140:143], v[214:217], v[14:17]
	v_mfma_f32_16x16x32_bf16 v[10:13], v[156:159], v[214:217], v[10:13]
	v_mfma_f32_16x16x32_bf16 v[62:65], v[152:155], v[184:187], v[62:65]
	v_mfma_f32_16x16x32_bf16 v[58:61], v[160:163], v[184:187], v[58:61]
	v_mfma_f32_16x16x32_bf16 v[46:49], v[152:155], v[192:195], v[46:49]
	v_mfma_f32_16x16x32_bf16 v[42:45], v[160:163], v[192:195], v[42:45]
	v_mfma_f32_16x16x32_bf16 v[30:33], v[152:155], v[210:213], v[30:33]
	v_mfma_f32_16x16x32_bf16 v[26:29], v[160:163], v[210:213], v[26:29]
	v_mfma_f32_16x16x32_bf16 v[14:17], v[152:155], v[218:221], v[14:17]
	v_mfma_f32_16x16x32_bf16 v[10:13], v[160:163], v[218:221], v[10:13]
	v_mfma_f32_16x16x32_bf16 v[54:57], v[164:167], v[180:183], v[54:57]
	v_mfma_f32_16x16x32_bf16 v[50:53], v[172:175], v[180:183], v[50:53]
	v_mfma_f32_16x16x32_bf16 v[38:41], v[164:167], v[188:191], v[38:41]
	v_mfma_f32_16x16x32_bf16 v[34:37], v[172:175], v[188:191], v[34:37]
	v_mfma_f32_16x16x32_bf16 v[22:25], v[164:167], v[206:209], v[22:25]
	v_mfma_f32_16x16x32_bf16 v[18:21], v[172:175], v[206:209], v[18:21]
	v_mfma_f32_16x16x32_bf16 v[6:9], v[164:167], v[214:217], v[6:9]
	v_mfma_f32_16x16x32_bf16 v[2:5], v[172:175], v[214:217], v[2:5]
	v_mfma_f32_16x16x32_bf16 v[54:57], v[168:171], v[184:187], v[54:57]
	v_mfma_f32_16x16x32_bf16 v[50:53], v[176:179], v[184:187], v[50:53]
	v_mfma_f32_16x16x32_bf16 v[38:41], v[168:171], v[192:195], v[38:41]
	v_mfma_f32_16x16x32_bf16 v[34:37], v[176:179], v[192:195], v[34:37]
	v_mfma_f32_16x16x32_bf16 v[22:25], v[168:171], v[210:213], v[22:25]
	v_mfma_f32_16x16x32_bf16 v[18:21], v[176:179], v[210:213], v[18:21]
	s_barrier
	v_mfma_f32_16x16x32_bf16 v[6:9], v[168:171], v[218:221], v[6:9]
	v_mfma_f32_16x16x32_bf16 v[2:5], v[176:179], v[218:221], v[2:5]
	s_add_u32 s24, s24, 0x80000
	s_addc_u32 s25, s25, 0
	s_add_u32 s100, s24, 0xfff80000
	s_addc_u32 s101, s25, -1
	s_add_i32 s2, 0, 0x18000
	s_add_i32 s45, 0, 0x1c000
	v_add_u32_e32 v160, s2, v148
	v_add_u32_e32 v176, s45, v148
	s_mov_b32 m0, s29
	ds_read_b128 v[140:143], v160
	ds_read_b128 v[152:155], v160 offset:1024
	ds_read_b128 v[156:159], v160 offset:2048
	ds_read_b128 v[160:163], v160 offset:3072
	global_load_lds_dwordx4 v134, s[100:101]
	s_mov_b32 m0, s30
	ds_read_b128 v[164:167], v176
	ds_read_b128 v[168:171], v176 offset:1024
	ds_read_b128 v[172:175], v176 offset:2048
	ds_read_b128 v[176:179], v176 offset:3072
	global_load_lds_dwordx4 v132, s[100:101]
	s_mov_b32 m0, s31
	ds_read_b128 v[180:183], v151 offset:32768
	ds_read_b128 v[184:187], v151 offset:33792
	ds_read_b128 v[188:191], v151 offset:34816
	ds_read_b128 v[192:195], v151 offset:35840
	global_load_lds_dwordx4 v134, s[24:25]
	s_mov_b32 m0, s33
	ds_read_b128 v[206:209], v151 offset:36864
	ds_read_b128 v[210:213], v151 offset:37888
	ds_read_b128 v[214:217], v151 offset:38912
	ds_read_b128 v[218:221], v151 offset:39936
	global_load_lds_dwordx4 v132, s[24:25]
	s_waitcnt vmcnt(8)
	s_waitcnt lgkmcnt(0)
	s_barrier
	s_waitcnt lgkmcnt(0)
	v_mfma_f32_16x16x32_bf16 v[126:129], v[140:143], v[180:183], v[126:129]
	v_mfma_f32_16x16x32_bf16 v[122:125], v[156:159], v[180:183], v[122:125]
	v_mfma_f32_16x16x32_bf16 v[110:113], v[140:143], v[188:191], v[110:113]
	v_mfma_f32_16x16x32_bf16 v[106:109], v[156:159], v[188:191], v[106:109]
	v_mfma_f32_16x16x32_bf16 v[94:97], v[140:143], v[206:209], v[94:97]
	v_mfma_f32_16x16x32_bf16 v[90:93], v[156:159], v[206:209], v[90:93]
	v_mfma_f32_16x16x32_bf16 v[78:81], v[140:143], v[214:217], v[78:81]
	v_mfma_f32_16x16x32_bf16 v[74:77], v[156:159], v[214:217], v[74:77]
	v_mfma_f32_16x16x32_bf16 v[126:129], v[152:155], v[184:187], v[126:129]
	v_mfma_f32_16x16x32_bf16 v[122:125], v[160:163], v[184:187], v[122:125]
	v_mfma_f32_16x16x32_bf16 v[110:113], v[152:155], v[192:195], v[110:113]
	v_mfma_f32_16x16x32_bf16 v[106:109], v[160:163], v[192:195], v[106:109]
	v_mfma_f32_16x16x32_bf16 v[94:97], v[152:155], v[210:213], v[94:97]
	v_mfma_f32_16x16x32_bf16 v[90:93], v[160:163], v[210:213], v[90:93]
	v_mfma_f32_16x16x32_bf16 v[78:81], v[152:155], v[218:221], v[78:81]
	v_mfma_f32_16x16x32_bf16 v[74:77], v[160:163], v[218:221], v[74:77]
	v_mfma_f32_16x16x32_bf16 v[118:121], v[164:167], v[180:183], v[118:121]
	v_mfma_f32_16x16x32_bf16 v[114:117], v[172:175], v[180:183], v[114:117]
	v_mfma_f32_16x16x32_bf16 v[102:105], v[164:167], v[188:191], v[102:105]
	v_mfma_f32_16x16x32_bf16 v[98:101], v[172:175], v[188:191], v[98:101]
	v_mfma_f32_16x16x32_bf16 v[86:89], v[164:167], v[206:209], v[86:89]
	v_mfma_f32_16x16x32_bf16 v[82:85], v[172:175], v[206:209], v[82:85]
	v_mfma_f32_16x16x32_bf16 v[70:73], v[164:167], v[214:217], v[70:73]
	v_mfma_f32_16x16x32_bf16 v[66:69], v[172:175], v[214:217], v[66:69]
	v_mfma_f32_16x16x32_bf16 v[118:121], v[168:171], v[184:187], v[118:121]
	v_mfma_f32_16x16x32_bf16 v[114:117], v[176:179], v[184:187], v[114:117]
	v_mfma_f32_16x16x32_bf16 v[102:105], v[168:171], v[192:195], v[102:105]
	v_mfma_f32_16x16x32_bf16 v[98:101], v[176:179], v[192:195], v[98:101]
	v_mfma_f32_16x16x32_bf16 v[86:89], v[168:171], v[210:213], v[86:89]
	v_mfma_f32_16x16x32_bf16 v[82:85], v[176:179], v[210:213], v[82:85]
	s_barrier
	v_mfma_f32_16x16x32_bf16 v[70:73], v[168:171], v[218:221], v[70:73]
	v_mfma_f32_16x16x32_bf16 v[66:69], v[176:179], v[218:221], v[66:69]
	s_add_u32 s20, s20, 0x80080
	s_addc_u32 s21, s21, 0
	s_add_u32 s46, s46, 0xfff80080
	s_addc_u32 s47, s47, -1
	s_add_i32 s2, s2, s28
	s_mov_b32 m0, s2
	ds_read_b128 v[180:183], v151 offset:49152
	ds_read_b128 v[184:187], v151 offset:50176
	global_load_lds_dwordx4 v0, s[46:47]
	s_add_i32 m0, s2, 0x2000
	s_add_i32 s2, s45, s28
	ds_read_b128 v[188:191], v151 offset:51200
	ds_read_b128 v[192:195], v151 offset:52224
	global_load_lds_dwordx4 v130, s[46:47]
	s_mov_b32 m0, s2
	ds_read_b128 v[206:209], v151 offset:53248
	ds_read_b128 v[210:213], v151 offset:54272
	global_load_lds_dwordx4 v0, s[20:21]
	s_add_i32 m0, s2, 0x2000
	ds_read_b128 v[214:217], v151 offset:55296
	ds_read_b128 v[218:221], v151 offset:56320
	global_load_lds_dwordx4 v130, s[20:21]
	s_waitcnt vmcnt(6)
	s_waitcnt lgkmcnt(0)
	s_barrier
	s_waitcnt lgkmcnt(0)
	v_mfma_f32_16x16x32_bf16 v[62:65], v[140:143], v[180:183], v[62:65]
	v_mfma_f32_16x16x32_bf16 v[58:61], v[156:159], v[180:183], v[58:61]
	v_mfma_f32_16x16x32_bf16 v[46:49], v[140:143], v[188:191], v[46:49]
	v_mfma_f32_16x16x32_bf16 v[42:45], v[156:159], v[188:191], v[42:45]
	v_mfma_f32_16x16x32_bf16 v[30:33], v[140:143], v[206:209], v[30:33]
	v_mfma_f32_16x16x32_bf16 v[26:29], v[156:159], v[206:209], v[26:29]
	v_mfma_f32_16x16x32_bf16 v[14:17], v[140:143], v[214:217], v[14:17]
	v_mfma_f32_16x16x32_bf16 v[10:13], v[156:159], v[214:217], v[10:13]
	v_mfma_f32_16x16x32_bf16 v[62:65], v[152:155], v[184:187], v[62:65]
	v_mfma_f32_16x16x32_bf16 v[58:61], v[160:163], v[184:187], v[58:61]
	v_mfma_f32_16x16x32_bf16 v[46:49], v[152:155], v[192:195], v[46:49]
	v_mfma_f32_16x16x32_bf16 v[42:45], v[160:163], v[192:195], v[42:45]
	v_mfma_f32_16x16x32_bf16 v[30:33], v[152:155], v[210:213], v[30:33]
	v_mfma_f32_16x16x32_bf16 v[26:29], v[160:163], v[210:213], v[26:29]
	v_mfma_f32_16x16x32_bf16 v[14:17], v[152:155], v[218:221], v[14:17]
	v_mfma_f32_16x16x32_bf16 v[10:13], v[160:163], v[218:221], v[10:13]
	v_mfma_f32_16x16x32_bf16 v[54:57], v[164:167], v[180:183], v[54:57]
	v_mfma_f32_16x16x32_bf16 v[50:53], v[172:175], v[180:183], v[50:53]
	v_mfma_f32_16x16x32_bf16 v[38:41], v[164:167], v[188:191], v[38:41]
	v_mfma_f32_16x16x32_bf16 v[34:37], v[172:175], v[188:191], v[34:37]
	v_mfma_f32_16x16x32_bf16 v[22:25], v[164:167], v[206:209], v[22:25]
	v_mfma_f32_16x16x32_bf16 v[18:21], v[172:175], v[206:209], v[18:21]
	v_mfma_f32_16x16x32_bf16 v[6:9], v[164:167], v[214:217], v[6:9]
	v_mfma_f32_16x16x32_bf16 v[2:5], v[172:175], v[214:217], v[2:5]
	v_mfma_f32_16x16x32_bf16 v[54:57], v[168:171], v[184:187], v[54:57]
	v_mfma_f32_16x16x32_bf16 v[50:53], v[176:179], v[184:187], v[50:53]
	v_mfma_f32_16x16x32_bf16 v[38:41], v[168:171], v[192:195], v[38:41]
	v_mfma_f32_16x16x32_bf16 v[34:37], v[176:179], v[192:195], v[34:37]
	v_mfma_f32_16x16x32_bf16 v[22:25], v[168:171], v[210:213], v[22:25]
	v_mfma_f32_16x16x32_bf16 v[18:21], v[176:179], v[210:213], v[18:21]
	s_barrier
	v_mfma_f32_16x16x32_bf16 v[6:9], v[168:171], v[218:221], v[6:9]
	v_mfma_f32_16x16x32_bf16 v[2:5], v[176:179], v[218:221], v[2:5]
	s_add_i32 s44, s44, 2
	s_add_u32 s22, s22, 0x100
	s_addc_u32 s23, s23, 0
	s_add_u32 s42, s42, 0x100
	s_addc_u32 s43, s43, 0
	s_cmp_gt_u32 s44, 29
	s_cbranch_scc0 .LBB0_140
	s_and_b64 vcc, exec, s[10:11]
	s_cbranch_vccz .LBB0_143
	s_barrier

.LBB0_168:
	s_add_u32 s2, s26, 0xfff80080
	s_addc_u32 s24, s27, -1
	s_add_i32 s50, 0, 0x10000
	s_cmp_eq_u32 s49, 28
	s_cselect_b32 s29, s19, s24
	s_cselect_b32 s28, s44, s2
	v_add_u32_e32 v144, s50, v152
	s_cselect_b32 s25, s17, s47
	s_cselect_b32 s24, s45, s46
	s_add_u32 s100, s26, 0xfff80000
	s_addc_u32 s101, s27, -1
	s_add_i32 s2, 0, 0x14000
	s_mov_b32 m0, s39
	ds_read_b128 v[140:143], v144
	ds_read_b128 v[148:151], v144 offset:1024
	ds_read_b128 v[156:159], v144 offset:2048
	ds_read_b128 v[160:163], v144 offset:3072
	global_load_lds_dwordx4 v136, s[100:101]
	s_mov_b32 m0, s40
	v_add_u32_e32 v144, s2, v152
	ds_read_b128 v[164:167], v144
	ds_read_b128 v[168:171], v144 offset:1024
	ds_read_b128 v[172:175], v144 offset:2048
	ds_read_b128 v[176:179], v144 offset:3072
	global_load_lds_dwordx4 v138, s[100:101]
	s_add_i32 m0, s33, 0xc000
	ds_read_b128 v[180:183], v155
	ds_read_b128 v[184:187], v155 offset:1024
	ds_read_b128 v[188:191], v155 offset:2048
	ds_read_b128 v[192:195], v155 offset:3072
	global_load_lds_dwordx4 v136, s[26:27]
	s_add_i32 m0, s33, 0xe000
	ds_read_b128 v[206:209], v155 offset:4096
	ds_read_b128 v[210:213], v155 offset:5120
	ds_read_b128 v[214:217], v155 offset:6144
	ds_read_b128 v[218:221], v155 offset:7168
	global_load_lds_dwordx4 v138, s[26:27]
	s_waitcnt vmcnt(8)
	s_waitcnt lgkmcnt(0)
	s_barrier
	s_waitcnt lgkmcnt(0)
	v_mfma_f32_16x16x32_bf16 v[122:125], v[140:143], v[180:183], v[122:125]
	v_mfma_f32_16x16x32_bf16 v[114:117], v[156:159], v[180:183], v[114:117]
	v_mfma_f32_16x16x32_bf16 v[106:109], v[140:143], v[188:191], v[106:109]
	v_mfma_f32_16x16x32_bf16 v[98:101], v[156:159], v[188:191], v[98:101]
	v_mfma_f32_16x16x32_bf16 v[90:93], v[140:143], v[206:209], v[90:93]
	v_mfma_f32_16x16x32_bf16 v[82:85], v[156:159], v[206:209], v[82:85]
	v_mfma_f32_16x16x32_bf16 v[74:77], v[140:143], v[214:217], v[74:77]
	v_mfma_f32_16x16x32_bf16 v[66:69], v[156:159], v[214:217], v[66:69]
	v_mfma_f32_16x16x32_bf16 v[122:125], v[148:151], v[184:187], v[122:125]
	v_mfma_f32_16x16x32_bf16 v[114:117], v[160:163], v[184:187], v[114:117]
	v_mfma_f32_16x16x32_bf16 v[106:109], v[148:151], v[192:195], v[106:109]
	v_mfma_f32_16x16x32_bf16 v[98:101], v[160:163], v[192:195], v[98:101]
	v_mfma_f32_16x16x32_bf16 v[90:93], v[148:151], v[210:213], v[90:93]
	v_mfma_f32_16x16x32_bf16 v[82:85], v[160:163], v[210:213], v[82:85]
	v_mfma_f32_16x16x32_bf16 v[74:77], v[148:151], v[218:221], v[74:77]
	v_mfma_f32_16x16x32_bf16 v[66:69], v[160:163], v[218:221], v[66:69]
	v_mfma_f32_16x16x32_bf16 v[126:129], v[164:167], v[180:183], v[126:129]
	v_mfma_f32_16x16x32_bf16 v[118:121], v[172:175], v[180:183], v[118:121]
	v_mfma_f32_16x16x32_bf16 v[110:113], v[164:167], v[188:191], v[110:113]
	v_mfma_f32_16x16x32_bf16 v[102:105], v[172:175], v[188:191], v[102:105]
	v_mfma_f32_16x16x32_bf16 v[94:97], v[164:167], v[206:209], v[94:97]
	v_mfma_f32_16x16x32_bf16 v[86:89], v[172:175], v[206:209], v[86:89]
	v_mfma_f32_16x16x32_bf16 v[78:81], v[164:167], v[214:217], v[78:81]
	v_mfma_f32_16x16x32_bf16 v[70:73], v[172:175], v[214:217], v[70:73]
	v_mfma_f32_16x16x32_bf16 v[126:129], v[168:171], v[184:187], v[126:129]
	v_mfma_f32_16x16x32_bf16 v[118:121], v[176:179], v[184:187], v[118:121]
	v_mfma_f32_16x16x32_bf16 v[110:113], v[168:171], v[192:195], v[110:113]
	v_mfma_f32_16x16x32_bf16 v[102:105], v[176:179], v[192:195], v[102:105]
	v_mfma_f32_16x16x32_bf16 v[94:97], v[168:171], v[210:213], v[94:97]
	v_mfma_f32_16x16x32_bf16 v[86:89], v[176:179], v[210:213], v[86:89]
	s_barrier
	v_mfma_f32_16x16x32_bf16 v[78:81], v[168:171], v[218:221], v[78:81]
	v_mfma_f32_16x16x32_bf16 v[70:73], v[176:179], v[218:221], v[70:73]
	s_add_u32 s52, s24, 0x80000
	s_addc_u32 s53, s25, 0
	s_add_i32 s50, s50, s35
	s_mov_b32 m0, s50
	ds_read_b128 v[180:183], v155 offset:16384
	ds_read_b128 v[184:187], v155 offset:17408
	global_load_lds_dwordx4 v0, s[24:25]
	s_add_i32 m0, s50, 0x2000
	s_add_i32 s2, s2, s35
	ds_read_b128 v[188:191], v155 offset:18432
	ds_read_b128 v[192:195], v155 offset:19456
	global_load_lds_dwordx4 v130, s[24:25]
	s_mov_b32 m0, s2
	ds_read_b128 v[206:209], v155 offset:20480
	ds_read_b128 v[210:213], v155 offset:21504
	global_load_lds_dwordx4 v0, s[52:53]
	s_add_i32 m0, s2, 0x2000
	ds_read_b128 v[214:217], v155 offset:22528
	ds_read_b128 v[218:221], v155 offset:23552
	global_load_lds_dwordx4 v130, s[52:53]
	s_waitcnt vmcnt(6)
	s_waitcnt lgkmcnt(0)
	s_barrier
	s_waitcnt lgkmcnt(0)
	v_mfma_f32_16x16x32_bf16 v[58:61], v[140:143], v[180:183], v[58:61]
	v_mfma_f32_16x16x32_bf16 v[50:53], v[156:159], v[180:183], v[50:53]
	v_mfma_f32_16x16x32_bf16 v[42:45], v[140:143], v[188:191], v[42:45]
	v_mfma_f32_16x16x32_bf16 v[34:37], v[156:159], v[188:191], v[34:37]
	v_mfma_f32_16x16x32_bf16 v[26:29], v[140:143], v[206:209], v[26:29]
	v_mfma_f32_16x16x32_bf16 v[18:21], v[156:159], v[206:209], v[18:21]
	v_mfma_f32_16x16x32_bf16 v[10:13], v[140:143], v[214:217], v[10:13]
	v_mfma_f32_16x16x32_bf16 v[6:9], v[156:159], v[214:217], v[6:9]
	v_mfma_f32_16x16x32_bf16 v[58:61], v[148:151], v[184:187], v[58:61]
	v_mfma_f32_16x16x32_bf16 v[50:53], v[160:163], v[184:187], v[50:53]
	v_mfma_f32_16x16x32_bf16 v[42:45], v[148:151], v[192:195], v[42:45]
	v_mfma_f32_16x16x32_bf16 v[34:37], v[160:163], v[192:195], v[34:37]
	v_mfma_f32_16x16x32_bf16 v[26:29], v[148:151], v[210:213], v[26:29]
	v_mfma_f32_16x16x32_bf16 v[18:21], v[160:163], v[210:213], v[18:21]
	v_mfma_f32_16x16x32_bf16 v[10:13], v[148:151], v[218:221], v[10:13]
	v_mfma_f32_16x16x32_bf16 v[6:9], v[160:163], v[218:221], v[6:9]
	v_mfma_f32_16x16x32_bf16 v[62:65], v[164:167], v[180:183], v[62:65]
	v_mfma_f32_16x16x32_bf16 v[54:57], v[172:175], v[180:183], v[54:57]
	v_mfma_f32_16x16x32_bf16 v[46:49], v[164:167], v[188:191], v[46:49]
	v_mfma_f32_16x16x32_bf16 v[38:41], v[172:175], v[188:191], v[38:41]
	v_mfma_f32_16x16x32_bf16 v[30:33], v[164:167], v[206:209], v[30:33]
	v_mfma_f32_16x16x32_bf16 v[22:25], v[172:175], v[206:209], v[22:25]
	v_mfma_f32_16x16x32_bf16 v[14:17], v[164:167], v[214:217], v[14:17]
	v_mfma_f32_16x16x32_bf16 v[2:5], v[172:175], v[214:217], v[2:5]
	v_mfma_f32_16x16x32_bf16 v[62:65], v[168:171], v[184:187], v[62:65]
	v_mfma_f32_16x16x32_bf16 v[54:57], v[176:179], v[184:187], v[54:57]
	v_mfma_f32_16x16x32_bf16 v[46:49], v[168:171], v[192:195], v[46:49]
	v_mfma_f32_16x16x32_bf16 v[38:41], v[176:179], v[192:195], v[38:41]
	v_mfma_f32_16x16x32_bf16 v[30:33], v[168:171], v[210:213], v[30:33]
	v_mfma_f32_16x16x32_bf16 v[22:25], v[176:179], v[210:213], v[22:25]
	s_barrier
	v_mfma_f32_16x16x32_bf16 v[14:17], v[168:171], v[218:221], v[14:17]
	v_mfma_f32_16x16x32_bf16 v[2:5], v[176:179], v[218:221], v[2:5]
	s_add_u32 s28, s28, 0x80000
	s_addc_u32 s29, s29, 0
	s_add_u32 s100, s28, 0xfff80000
	s_addc_u32 s101, s29, -1
	s_add_i32 s2, 0, 0x18000
	s_add_i32 s50, 0, 0x1c000
	v_add_u32_e32 v160, s2, v152
	v_add_u32_e32 v176, s50, v152
	s_mov_b32 m0, s33
	ds_read_b128 v[140:143], v160
	ds_read_b128 v[148:151], v160 offset:1024
	ds_read_b128 v[156:159], v160 offset:2048
	ds_read_b128 v[160:163], v160 offset:3072
	global_load_lds_dwordx4 v134, s[100:101]
	s_mov_b32 m0, s36
	ds_read_b128 v[164:167], v176
	ds_read_b128 v[168:171], v176 offset:1024
	ds_read_b128 v[172:175], v176 offset:2048
	ds_read_b128 v[176:179], v176 offset:3072
	global_load_lds_dwordx4 v132, s[100:101]
	s_mov_b32 m0, s37
	ds_read_b128 v[180:183], v155 offset:32768
	ds_read_b128 v[184:187], v155 offset:33792
	ds_read_b128 v[188:191], v155 offset:34816
	ds_read_b128 v[192:195], v155 offset:35840
	global_load_lds_dwordx4 v134, s[28:29]
	s_mov_b32 m0, s38
	ds_read_b128 v[206:209], v155 offset:36864
	ds_read_b128 v[210:213], v155 offset:37888
	ds_read_b128 v[214:217], v155 offset:38912
	ds_read_b128 v[218:221], v155 offset:39936
	global_load_lds_dwordx4 v132, s[28:29]
	s_waitcnt vmcnt(8)
	s_waitcnt lgkmcnt(0)
	s_barrier
	s_waitcnt lgkmcnt(0)
	v_mfma_f32_16x16x32_bf16 v[122:125], v[140:143], v[180:183], v[122:125]
	v_mfma_f32_16x16x32_bf16 v[114:117], v[156:159], v[180:183], v[114:117]
	v_mfma_f32_16x16x32_bf16 v[106:109], v[140:143], v[188:191], v[106:109]
	v_mfma_f32_16x16x32_bf16 v[98:101], v[156:159], v[188:191], v[98:101]
	v_mfma_f32_16x16x32_bf16 v[90:93], v[140:143], v[206:209], v[90:93]
	v_mfma_f32_16x16x32_bf16 v[82:85], v[156:159], v[206:209], v[82:85]
	v_mfma_f32_16x16x32_bf16 v[74:77], v[140:143], v[214:217], v[74:77]
	v_mfma_f32_16x16x32_bf16 v[66:69], v[156:159], v[214:217], v[66:69]
	v_mfma_f32_16x16x32_bf16 v[122:125], v[148:151], v[184:187], v[122:125]
	v_mfma_f32_16x16x32_bf16 v[114:117], v[160:163], v[184:187], v[114:117]
	v_mfma_f32_16x16x32_bf16 v[106:109], v[148:151], v[192:195], v[106:109]
	v_mfma_f32_16x16x32_bf16 v[98:101], v[160:163], v[192:195], v[98:101]
	v_mfma_f32_16x16x32_bf16 v[90:93], v[148:151], v[210:213], v[90:93]
	v_mfma_f32_16x16x32_bf16 v[82:85], v[160:163], v[210:213], v[82:85]
	v_mfma_f32_16x16x32_bf16 v[74:77], v[148:151], v[218:221], v[74:77]
	v_mfma_f32_16x16x32_bf16 v[66:69], v[160:163], v[218:221], v[66:69]
	v_mfma_f32_16x16x32_bf16 v[126:129], v[164:167], v[180:183], v[126:129]
	v_mfma_f32_16x16x32_bf16 v[118:121], v[172:175], v[180:183], v[118:121]
	v_mfma_f32_16x16x32_bf16 v[110:113], v[164:167], v[188:191], v[110:113]
	v_mfma_f32_16x16x32_bf16 v[102:105], v[172:175], v[188:191], v[102:105]
	v_mfma_f32_16x16x32_bf16 v[94:97], v[164:167], v[206:209], v[94:97]
	v_mfma_f32_16x16x32_bf16 v[86:89], v[172:175], v[206:209], v[86:89]
	v_mfma_f32_16x16x32_bf16 v[78:81], v[164:167], v[214:217], v[78:81]
	v_mfma_f32_16x16x32_bf16 v[70:73], v[172:175], v[214:217], v[70:73]
	v_mfma_f32_16x16x32_bf16 v[126:129], v[168:171], v[184:187], v[126:129]
	v_mfma_f32_16x16x32_bf16 v[118:121], v[176:179], v[184:187], v[118:121]
	v_mfma_f32_16x16x32_bf16 v[110:113], v[168:171], v[192:195], v[110:113]
	v_mfma_f32_16x16x32_bf16 v[102:105], v[176:179], v[192:195], v[102:105]
	v_mfma_f32_16x16x32_bf16 v[94:97], v[168:171], v[210:213], v[94:97]
	v_mfma_f32_16x16x32_bf16 v[86:89], v[176:179], v[210:213], v[86:89]
	s_barrier
	v_mfma_f32_16x16x32_bf16 v[78:81], v[168:171], v[218:221], v[78:81]
	v_mfma_f32_16x16x32_bf16 v[70:73], v[176:179], v[218:221], v[70:73]
	s_add_u32 s24, s24, 0x80080
	s_addc_u32 s25, s25, 0
	s_add_u32 s52, s52, 0xfff80080
	s_addc_u32 s53, s53, -1
	s_add_i32 s2, s2, s35
	s_mov_b32 m0, s2
	ds_read_b128 v[180:183], v155 offset:49152
	ds_read_b128 v[184:187], v155 offset:50176
	global_load_lds_dwordx4 v0, s[52:53]
	s_add_i32 m0, s2, 0x2000
	s_add_i32 s2, s50, s35
	ds_read_b128 v[188:191], v155 offset:51200
	ds_read_b128 v[192:195], v155 offset:52224
	global_load_lds_dwordx4 v130, s[52:53]
	s_mov_b32 m0, s2
	ds_read_b128 v[206:209], v155 offset:53248
	ds_read_b128 v[210:213], v155 offset:54272
	global_load_lds_dwordx4 v0, s[24:25]
	s_add_i32 m0, s2, 0x2000
	ds_read_b128 v[214:217], v155 offset:55296
	ds_read_b128 v[218:221], v155 offset:56320
	global_load_lds_dwordx4 v130, s[24:25]
	s_waitcnt vmcnt(6)
	s_waitcnt lgkmcnt(0)
	s_barrier
	s_waitcnt lgkmcnt(0)
	v_mfma_f32_16x16x32_bf16 v[58:61], v[140:143], v[180:183], v[58:61]
	v_mfma_f32_16x16x32_bf16 v[50:53], v[156:159], v[180:183], v[50:53]
	v_mfma_f32_16x16x32_bf16 v[42:45], v[140:143], v[188:191], v[42:45]
	v_mfma_f32_16x16x32_bf16 v[34:37], v[156:159], v[188:191], v[34:37]
	v_mfma_f32_16x16x32_bf16 v[26:29], v[140:143], v[206:209], v[26:29]
	v_mfma_f32_16x16x32_bf16 v[18:21], v[156:159], v[206:209], v[18:21]
	v_mfma_f32_16x16x32_bf16 v[10:13], v[140:143], v[214:217], v[10:13]
	v_mfma_f32_16x16x32_bf16 v[6:9], v[156:159], v[214:217], v[6:9]
	v_mfma_f32_16x16x32_bf16 v[58:61], v[148:151], v[184:187], v[58:61]
	v_mfma_f32_16x16x32_bf16 v[50:53], v[160:163], v[184:187], v[50:53]
	v_mfma_f32_16x16x32_bf16 v[42:45], v[148:151], v[192:195], v[42:45]
	v_mfma_f32_16x16x32_bf16 v[34:37], v[160:163], v[192:195], v[34:37]
	v_mfma_f32_16x16x32_bf16 v[26:29], v[148:151], v[210:213], v[26:29]
	v_mfma_f32_16x16x32_bf16 v[18:21], v[160:163], v[210:213], v[18:21]
	v_mfma_f32_16x16x32_bf16 v[10:13], v[148:151], v[218:221], v[10:13]
	v_mfma_f32_16x16x32_bf16 v[6:9], v[160:163], v[218:221], v[6:9]
	v_mfma_f32_16x16x32_bf16 v[62:65], v[164:167], v[180:183], v[62:65]
	v_mfma_f32_16x16x32_bf16 v[54:57], v[172:175], v[180:183], v[54:57]
	v_mfma_f32_16x16x32_bf16 v[46:49], v[164:167], v[188:191], v[46:49]
	v_mfma_f32_16x16x32_bf16 v[38:41], v[172:175], v[188:191], v[38:41]
	v_mfma_f32_16x16x32_bf16 v[30:33], v[164:167], v[206:209], v[30:33]
	v_mfma_f32_16x16x32_bf16 v[22:25], v[172:175], v[206:209], v[22:25]
	v_mfma_f32_16x16x32_bf16 v[14:17], v[164:167], v[214:217], v[14:17]
	v_mfma_f32_16x16x32_bf16 v[2:5], v[172:175], v[214:217], v[2:5]
	v_mfma_f32_16x16x32_bf16 v[62:65], v[168:171], v[184:187], v[62:65]
	v_mfma_f32_16x16x32_bf16 v[54:57], v[176:179], v[184:187], v[54:57]
	v_mfma_f32_16x16x32_bf16 v[46:49], v[168:171], v[192:195], v[46:49]
	v_mfma_f32_16x16x32_bf16 v[38:41], v[176:179], v[192:195], v[38:41]
	v_mfma_f32_16x16x32_bf16 v[30:33], v[168:171], v[210:213], v[30:33]
	v_mfma_f32_16x16x32_bf16 v[22:25], v[176:179], v[210:213], v[22:25]
	s_barrier
	v_mfma_f32_16x16x32_bf16 v[14:17], v[168:171], v[218:221], v[14:17]
	v_mfma_f32_16x16x32_bf16 v[2:5], v[176:179], v[218:221], v[2:5]
	s_add_i32 s49, s49, 2
	s_add_u32 s26, s26, 0x100
	s_addc_u32 s27, s27, 0
	s_add_u32 s46, s46, 0x100
	s_addc_u32 s47, s47, 0
	s_cmp_gt_u32 s49, 29
	s_cbranch_scc0 .LBB0_168
	s_and_b64 vcc, exec, s[14:15]
	s_cbranch_vccz .LBB0_171
	s_barrier

.LBB0_281:
	s_add_u32 s20, s18, 0x100
	s_addc_u32 s21, s19, 0
	s_add_i32 s2, 0, 0x10000
	s_cmpk_eq_i32 s42, 0x52
	s_cselect_b32 s25, s11, s21
	s_cselect_b32 s24, s10, s20
	s_cselect_b32 s23, s17, s41
	s_cselect_b32 s22, s16, s40
	s_add_u32 s100, s18, 0xffea8000
	s_addc_u32 s101, s19, -1
	s_add_i32 s43, 0, 0x14000
	v_add_u32_e32 v142, s2, v226
	v_add_u32_e32 v160, s43, v226
	s_mov_b32 m0, s36
	ds_read_b128 v[126:129], v142
	ds_read_b128 v[134:137], v142 offset:1024
	ds_read_b128 v[138:141], v142 offset:2048
	ds_read_b128 v[142:145], v142 offset:3072
	global_load_lds_dwordx4 v194, s[100:101]
	s_mov_b32 m0, s37
	ds_read_b128 v[148:151], v160
	ds_read_b128 v[152:155], v160 offset:1024
	ds_read_b128 v[156:159], v160 offset:2048
	ds_read_b128 v[160:163], v160 offset:3072
	global_load_lds_dwordx4 v206, s[100:101]
	s_add_i32 m0, s26, 0xc000
	ds_read_b128 v[164:167], v228
	ds_read_b128 v[168:171], v228 offset:1024
	ds_read_b128 v[172:175], v228 offset:2048
	ds_read_b128 v[176:179], v228 offset:3072
	global_load_lds_dwordx4 v194, s[18:19]
	s_add_i32 m0, s26, 0xe000
	ds_read_b128 v[180:183], v228 offset:4096
	ds_read_b128 v[184:187], v228 offset:5120
	ds_read_b128 v[208:211], v228 offset:6144
	ds_read_b128 v[212:215], v228 offset:7168
	global_load_lds_dwordx4 v206, s[18:19]
	s_waitcnt vmcnt(8)
	s_waitcnt lgkmcnt(0)
	s_barrier
	s_waitcnt lgkmcnt(0)
	v_mfma_f32_16x16x32_bf16 v[130:133], v[126:129], v[164:167], v[130:133]
	v_mfma_f32_16x16x32_bf16 v[122:125], v[138:141], v[164:167], v[122:125]
	v_mfma_f32_16x16x32_bf16 v[110:113], v[126:129], v[172:175], v[110:113]
	v_mfma_f32_16x16x32_bf16 v[106:109], v[138:141], v[172:175], v[106:109]
	v_mfma_f32_16x16x32_bf16 v[94:97], v[126:129], v[180:183], v[94:97]
	v_mfma_f32_16x16x32_bf16 v[90:93], v[138:141], v[180:183], v[90:93]
	v_mfma_f32_16x16x32_bf16 v[78:81], v[126:129], v[208:211], v[78:81]
	v_mfma_f32_16x16x32_bf16 v[74:77], v[138:141], v[208:211], v[74:77]
	v_mfma_f32_16x16x32_bf16 v[130:133], v[134:137], v[168:171], v[130:133]
	v_mfma_f32_16x16x32_bf16 v[122:125], v[142:145], v[168:171], v[122:125]
	v_mfma_f32_16x16x32_bf16 v[110:113], v[134:137], v[176:179], v[110:113]
	v_mfma_f32_16x16x32_bf16 v[106:109], v[142:145], v[176:179], v[106:109]
	v_mfma_f32_16x16x32_bf16 v[94:97], v[134:137], v[184:187], v[94:97]
	v_mfma_f32_16x16x32_bf16 v[90:93], v[142:145], v[184:187], v[90:93]
	v_mfma_f32_16x16x32_bf16 v[78:81], v[134:137], v[212:215], v[78:81]
	v_mfma_f32_16x16x32_bf16 v[74:77], v[142:145], v[212:215], v[74:77]
	v_mfma_f32_16x16x32_bf16 v[118:121], v[148:151], v[164:167], v[118:121]
	v_mfma_f32_16x16x32_bf16 v[114:117], v[156:159], v[164:167], v[114:117]
	v_mfma_f32_16x16x32_bf16 v[102:105], v[148:151], v[172:175], v[102:105]
	v_mfma_f32_16x16x32_bf16 v[98:101], v[156:159], v[172:175], v[98:101]
	v_mfma_f32_16x16x32_bf16 v[86:89], v[148:151], v[180:183], v[86:89]
	v_mfma_f32_16x16x32_bf16 v[82:85], v[156:159], v[180:183], v[82:85]
	v_mfma_f32_16x16x32_bf16 v[70:73], v[148:151], v[208:211], v[70:73]
	v_mfma_f32_16x16x32_bf16 v[66:69], v[156:159], v[208:211], v[66:69]
	v_mfma_f32_16x16x32_bf16 v[118:121], v[152:155], v[168:171], v[118:121]
	v_mfma_f32_16x16x32_bf16 v[114:117], v[160:163], v[168:171], v[114:117]
	v_mfma_f32_16x16x32_bf16 v[102:105], v[152:155], v[176:179], v[102:105]
	v_mfma_f32_16x16x32_bf16 v[98:101], v[160:163], v[176:179], v[98:101]
	v_mfma_f32_16x16x32_bf16 v[86:89], v[152:155], v[184:187], v[86:89]
	v_mfma_f32_16x16x32_bf16 v[82:85], v[160:163], v[184:187], v[82:85]
	s_barrier
	v_mfma_f32_16x16x32_bf16 v[70:73], v[152:155], v[212:215], v[70:73]
	v_mfma_f32_16x16x32_bf16 v[66:69], v[160:163], v[212:215], v[66:69]
	s_add_u32 s18, s22, 0x158000
	s_addc_u32 s19, s23, 0
	s_add_i32 s2, s2, s1
	s_mov_b32 m0, s2
	ds_read_b128 v[164:167], v228 offset:16384
	ds_read_b128 v[168:171], v228 offset:17408
	global_load_lds_dwordx4 v0, s[22:23]
	s_add_i32 m0, s2, 0x2000
	s_add_i32 s2, s43, s1
	ds_read_b128 v[172:175], v228 offset:18432
	ds_read_b128 v[176:179], v228 offset:19456
	global_load_lds_dwordx4 v188, s[22:23]
	s_mov_b32 m0, s2
	ds_read_b128 v[180:183], v228 offset:20480
	ds_read_b128 v[184:187], v228 offset:21504
	global_load_lds_dwordx4 v0, s[18:19]
	s_add_i32 m0, s2, 0x2000
	ds_read_b128 v[208:211], v228 offset:22528
	ds_read_b128 v[212:215], v228 offset:23552
	global_load_lds_dwordx4 v188, s[18:19]
	s_waitcnt vmcnt(6)
	s_waitcnt lgkmcnt(0)
	s_barrier
	s_waitcnt lgkmcnt(0)
	v_mfma_f32_16x16x32_bf16 v[62:65], v[126:129], v[164:167], v[62:65]
	v_mfma_f32_16x16x32_bf16 v[58:61], v[138:141], v[164:167], v[58:61]
	v_mfma_f32_16x16x32_bf16 v[46:49], v[126:129], v[172:175], v[46:49]
	v_mfma_f32_16x16x32_bf16 v[42:45], v[138:141], v[172:175], v[42:45]
	v_mfma_f32_16x16x32_bf16 v[30:33], v[126:129], v[180:183], v[30:33]
	v_mfma_f32_16x16x32_bf16 v[26:29], v[138:141], v[180:183], v[26:29]
	v_mfma_f32_16x16x32_bf16 v[14:17], v[126:129], v[208:211], v[14:17]
	v_mfma_f32_16x16x32_bf16 v[10:13], v[138:141], v[208:211], v[10:13]
	v_mfma_f32_16x16x32_bf16 v[62:65], v[134:137], v[168:171], v[62:65]
	v_mfma_f32_16x16x32_bf16 v[58:61], v[142:145], v[168:171], v[58:61]
	v_mfma_f32_16x16x32_bf16 v[46:49], v[134:137], v[176:179], v[46:49]
	v_mfma_f32_16x16x32_bf16 v[42:45], v[142:145], v[176:179], v[42:45]
	v_mfma_f32_16x16x32_bf16 v[30:33], v[134:137], v[184:187], v[30:33]
	v_mfma_f32_16x16x32_bf16 v[26:29], v[142:145], v[184:187], v[26:29]
	v_mfma_f32_16x16x32_bf16 v[14:17], v[134:137], v[212:215], v[14:17]
	v_mfma_f32_16x16x32_bf16 v[10:13], v[142:145], v[212:215], v[10:13]
	v_mfma_f32_16x16x32_bf16 v[54:57], v[148:151], v[164:167], v[54:57]
	v_mfma_f32_16x16x32_bf16 v[50:53], v[156:159], v[164:167], v[50:53]
	v_mfma_f32_16x16x32_bf16 v[38:41], v[148:151], v[172:175], v[38:41]
	v_mfma_f32_16x16x32_bf16 v[34:37], v[156:159], v[172:175], v[34:37]
	v_mfma_f32_16x16x32_bf16 v[22:25], v[148:151], v[180:183], v[22:25]
	v_mfma_f32_16x16x32_bf16 v[18:21], v[156:159], v[180:183], v[18:21]
	v_mfma_f32_16x16x32_bf16 v[6:9], v[148:151], v[208:211], v[6:9]
	v_mfma_f32_16x16x32_bf16 v[2:5], v[156:159], v[208:211], v[2:5]
	v_mfma_f32_16x16x32_bf16 v[54:57], v[152:155], v[168:171], v[54:57]
	v_mfma_f32_16x16x32_bf16 v[50:53], v[160:163], v[168:171], v[50:53]
	v_mfma_f32_16x16x32_bf16 v[38:41], v[152:155], v[176:179], v[38:41]
	v_mfma_f32_16x16x32_bf16 v[34:37], v[160:163], v[176:179], v[34:37]
	v_mfma_f32_16x16x32_bf16 v[22:25], v[152:155], v[184:187], v[22:25]
	v_mfma_f32_16x16x32_bf16 v[18:21], v[160:163], v[184:187], v[18:21]
	s_barrier
	v_mfma_f32_16x16x32_bf16 v[6:9], v[152:155], v[212:215], v[6:9]
	v_mfma_f32_16x16x32_bf16 v[2:5], v[160:163], v[212:215], v[2:5]
	s_add_u32 s18, s24, 0x158000
	s_addc_u32 s19, s25, 0
	s_add_i32 s2, 0, 0x18000
	s_add_i32 s43, 0, 0x1c000
	v_add_u32_e32 v142, s2, v226
	v_add_u32_e32 v160, s43, v226
	s_mov_b32 m0, s26
	ds_read_b128 v[126:129], v142
	ds_read_b128 v[134:137], v142 offset:1024
	ds_read_b128 v[138:141], v142 offset:2048
	ds_read_b128 v[142:145], v142 offset:3072
	global_load_lds_dwordx4 v192, s[24:25]
	s_mov_b32 m0, s27
	ds_read_b128 v[148:151], v160
	ds_read_b128 v[152:155], v160 offset:1024
	ds_read_b128 v[156:159], v160 offset:2048
	ds_read_b128 v[160:163], v160 offset:3072
	global_load_lds_dwordx4 v190, s[24:25]
	s_mov_b32 m0, s30
	ds_read_b128 v[164:167], v228 offset:32768
	ds_read_b128 v[168:171], v228 offset:33792
	ds_read_b128 v[172:175], v228 offset:34816
	ds_read_b128 v[176:179], v228 offset:35840
	global_load_lds_dwordx4 v192, s[18:19]
	s_mov_b32 m0, s31
	ds_read_b128 v[180:183], v228 offset:36864
	ds_read_b128 v[184:187], v228 offset:37888
	ds_read_b128 v[208:211], v228 offset:38912
	ds_read_b128 v[212:215], v228 offset:39936
	global_load_lds_dwordx4 v190, s[18:19]
	s_waitcnt vmcnt(8)
	s_waitcnt lgkmcnt(0)
	s_barrier
	s_waitcnt lgkmcnt(0)
	v_mfma_f32_16x16x32_bf16 v[130:133], v[126:129], v[164:167], v[130:133]
	v_mfma_f32_16x16x32_bf16 v[122:125], v[138:141], v[164:167], v[122:125]
	v_mfma_f32_16x16x32_bf16 v[110:113], v[126:129], v[172:175], v[110:113]
	v_mfma_f32_16x16x32_bf16 v[106:109], v[138:141], v[172:175], v[106:109]
	v_mfma_f32_16x16x32_bf16 v[94:97], v[126:129], v[180:183], v[94:97]
	v_mfma_f32_16x16x32_bf16 v[90:93], v[138:141], v[180:183], v[90:93]
	v_mfma_f32_16x16x32_bf16 v[78:81], v[126:129], v[208:211], v[78:81]
	v_mfma_f32_16x16x32_bf16 v[74:77], v[138:141], v[208:211], v[74:77]
	v_mfma_f32_16x16x32_bf16 v[130:133], v[134:137], v[168:171], v[130:133]
	v_mfma_f32_16x16x32_bf16 v[122:125], v[142:145], v[168:171], v[122:125]
	v_mfma_f32_16x16x32_bf16 v[110:113], v[134:137], v[176:179], v[110:113]
	v_mfma_f32_16x16x32_bf16 v[106:109], v[142:145], v[176:179], v[106:109]
	v_mfma_f32_16x16x32_bf16 v[94:97], v[134:137], v[184:187], v[94:97]
	v_mfma_f32_16x16x32_bf16 v[90:93], v[142:145], v[184:187], v[90:93]
	v_mfma_f32_16x16x32_bf16 v[78:81], v[134:137], v[212:215], v[78:81]
	v_mfma_f32_16x16x32_bf16 v[74:77], v[142:145], v[212:215], v[74:77]
	v_mfma_f32_16x16x32_bf16 v[118:121], v[148:151], v[164:167], v[118:121]
	v_mfma_f32_16x16x32_bf16 v[114:117], v[156:159], v[164:167], v[114:117]
	v_mfma_f32_16x16x32_bf16 v[102:105], v[148:151], v[172:175], v[102:105]
	v_mfma_f32_16x16x32_bf16 v[98:101], v[156:159], v[172:175], v[98:101]
	v_mfma_f32_16x16x32_bf16 v[86:89], v[148:151], v[180:183], v[86:89]
	v_mfma_f32_16x16x32_bf16 v[82:85], v[156:159], v[180:183], v[82:85]
	v_mfma_f32_16x16x32_bf16 v[70:73], v[148:151], v[208:211], v[70:73]
	v_mfma_f32_16x16x32_bf16 v[66:69], v[156:159], v[208:211], v[66:69]
	v_mfma_f32_16x16x32_bf16 v[118:121], v[152:155], v[168:171], v[118:121]
	v_mfma_f32_16x16x32_bf16 v[114:117], v[160:163], v[168:171], v[114:117]
	v_mfma_f32_16x16x32_bf16 v[102:105], v[152:155], v[176:179], v[102:105]
	v_mfma_f32_16x16x32_bf16 v[98:101], v[160:163], v[176:179], v[98:101]
	v_mfma_f32_16x16x32_bf16 v[86:89], v[152:155], v[184:187], v[86:89]
	v_mfma_f32_16x16x32_bf16 v[82:85], v[160:163], v[184:187], v[82:85]
	s_barrier
	v_mfma_f32_16x16x32_bf16 v[70:73], v[152:155], v[212:215], v[70:73]
	v_mfma_f32_16x16x32_bf16 v[66:69], v[160:163], v[212:215], v[66:69]
	s_add_u32 s18, s22, 0x158080
	s_addc_u32 s19, s23, 0
	s_add_u32 s22, s22, 0x80
	s_addc_u32 s23, s23, 0
	s_add_i32 s2, s2, s1
	s_mov_b32 m0, s2
	ds_read_b128 v[164:167], v228 offset:49152
	ds_read_b128 v[168:171], v228 offset:50176
	global_load_lds_dwordx4 v0, s[22:23]
	s_add_i32 m0, s2, 0x2000
	s_add_i32 s2, s43, s1
	ds_read_b128 v[172:175], v228 offset:51200
	ds_read_b128 v[176:179], v228 offset:52224
	global_load_lds_dwordx4 v188, s[22:23]
	s_mov_b32 m0, s2
	ds_read_b128 v[180:183], v228 offset:53248
	ds_read_b128 v[184:187], v228 offset:54272
	global_load_lds_dwordx4 v0, s[18:19]
	s_add_i32 m0, s2, 0x2000
	ds_read_b128 v[208:211], v228 offset:55296
	ds_read_b128 v[212:215], v228 offset:56320
	global_load_lds_dwordx4 v188, s[18:19]
	s_waitcnt vmcnt(6)
	s_waitcnt lgkmcnt(0)
	s_barrier
	s_waitcnt lgkmcnt(0)
	v_mfma_f32_16x16x32_bf16 v[62:65], v[126:129], v[164:167], v[62:65]
	v_mfma_f32_16x16x32_bf16 v[58:61], v[138:141], v[164:167], v[58:61]
	v_mfma_f32_16x16x32_bf16 v[46:49], v[126:129], v[172:175], v[46:49]
	v_mfma_f32_16x16x32_bf16 v[42:45], v[138:141], v[172:175], v[42:45]
	v_mfma_f32_16x16x32_bf16 v[30:33], v[126:129], v[180:183], v[30:33]
	v_mfma_f32_16x16x32_bf16 v[26:29], v[138:141], v[180:183], v[26:29]
	v_mfma_f32_16x16x32_bf16 v[14:17], v[126:129], v[208:211], v[14:17]
	v_mfma_f32_16x16x32_bf16 v[10:13], v[138:141], v[208:211], v[10:13]
	v_mfma_f32_16x16x32_bf16 v[62:65], v[134:137], v[168:171], v[62:65]
	v_mfma_f32_16x16x32_bf16 v[58:61], v[142:145], v[168:171], v[58:61]
	v_mfma_f32_16x16x32_bf16 v[46:49], v[134:137], v[176:179], v[46:49]
	v_mfma_f32_16x16x32_bf16 v[42:45], v[142:145], v[176:179], v[42:45]
	v_mfma_f32_16x16x32_bf16 v[30:33], v[134:137], v[184:187], v[30:33]
	v_mfma_f32_16x16x32_bf16 v[26:29], v[142:145], v[184:187], v[26:29]
	v_mfma_f32_16x16x32_bf16 v[14:17], v[134:137], v[212:215], v[14:17]
	v_mfma_f32_16x16x32_bf16 v[10:13], v[142:145], v[212:215], v[10:13]
	v_mfma_f32_16x16x32_bf16 v[54:57], v[148:151], v[164:167], v[54:57]
	v_mfma_f32_16x16x32_bf16 v[50:53], v[156:159], v[164:167], v[50:53]
	v_mfma_f32_16x16x32_bf16 v[38:41], v[148:151], v[172:175], v[38:41]
	v_mfma_f32_16x16x32_bf16 v[34:37], v[156:159], v[172:175], v[34:37]
	v_mfma_f32_16x16x32_bf16 v[22:25], v[148:151], v[180:183], v[22:25]
	v_mfma_f32_16x16x32_bf16 v[18:21], v[156:159], v[180:183], v[18:21]
	v_mfma_f32_16x16x32_bf16 v[6:9], v[148:151], v[208:211], v[6:9]
	v_mfma_f32_16x16x32_bf16 v[2:5], v[156:159], v[208:211], v[2:5]
	v_mfma_f32_16x16x32_bf16 v[54:57], v[152:155], v[168:171], v[54:57]
	v_mfma_f32_16x16x32_bf16 v[50:53], v[160:163], v[168:171], v[50:53]
	v_mfma_f32_16x16x32_bf16 v[38:41], v[152:155], v[176:179], v[38:41]
	v_mfma_f32_16x16x32_bf16 v[34:37], v[160:163], v[176:179], v[34:37]
	v_mfma_f32_16x16x32_bf16 v[22:25], v[152:155], v[184:187], v[22:25]
	v_mfma_f32_16x16x32_bf16 v[18:21], v[160:163], v[184:187], v[18:21]
	s_barrier
	v_mfma_f32_16x16x32_bf16 v[6:9], v[152:155], v[212:215], v[6:9]
	v_mfma_f32_16x16x32_bf16 v[2:5], v[160:163], v[212:215], v[2:5]
	s_add_i32 s42, s42, 2
	s_add_u32 s40, s40, 0x100
	s_addc_u32 s41, s41, 0
	s_cmpk_gt_u32 s42, 0x53
	s_mov_b64 s[18:19], s[20:21]
	s_cbranch_scc0 .LBB0_281
	s_nop 0
	s_nop 0
	s_nop 0
	v_lshl_or_b32 v210, s3, 8, v227
	v_lshl_add_u32 v224, s34, 8, v147
	v_ashrrev_i32_e32 v211, 31, v210
	v_lshlrev_b64 v[126:127], 1, v[210:211]
	v_ashrrev_i32_e32 v225, 31, v224
	v_lshl_add_u64 v[128:129], s[12:13], 0, v[126:127]
	v_lshlrev_b64 v[134:135], 12, v[224:225]
	v_lshl_add_u64 v[136:137], v[128:129], 0, v[134:135]
	global_load_dwordx4 v[240:243], v[136:137], off
	global_load_dwordx4 v[244:247], v[136:137], off offset:256
	v_or_b32_e32 v222, 16, v224
	v_or_b32_e32 v220, 32, v224
	v_or_b32_e32 v218, 48, v224
	v_add_u32_e32 v216, 0x80, v224
	v_add_u32_e32 v214, 0x90, v224
	v_add_u32_e32 v212, 0xa0, v224
	v_add_u32_e32 v208, 0xb0, v224
	v_ashrrev_i32_e32 v223, 31, v222
	v_ashrrev_i32_e32 v221, 31, v220
	v_ashrrev_i32_e32 v219, 31, v218
	v_ashrrev_i32_e32 v217, 31, v216
	v_ashrrev_i32_e32 v215, 31, v214
	v_ashrrev_i32_e32 v213, 31, v212
	v_ashrrev_i32_e32 v209, 31, v208
	v_lshlrev_b64 v[136:137], 12, v[222:223]
	v_lshlrev_b64 v[138:139], 12, v[220:221]
	v_lshlrev_b64 v[140:141], 12, v[218:219]
	v_lshlrev_b64 v[142:143], 12, v[216:217]
	v_lshlrev_b64 v[144:145], 12, v[214:215]
	v_lshlrev_b64 v[148:149], 12, v[212:213]
	v_lshlrev_b64 v[150:151], 12, v[208:209]
	v_lshl_add_u64 v[134:135], s[12:13], 0, v[134:135]
	v_lshl_add_u64 v[136:137], v[128:129], 0, v[136:137]
	v_lshl_add_u64 v[138:139], v[128:129], 0, v[138:139]
	v_lshl_add_u64 v[140:141], v[128:129], 0, v[140:141]
	v_lshl_add_u64 v[142:143], v[128:129], 0, v[142:143]
	v_lshl_add_u64 v[144:145], v[128:129], 0, v[144:145]
	v_lshl_add_u64 v[248:249], v[128:129], 0, v[148:149]
	v_lshl_add_u64 v[128:129], v[128:129], 0, v[150:151]
	v_lshl_add_u64 v[250:251], v[134:135], 0, v[126:127]
	global_load_dwordx4 v[184:187], v[136:137], off
	global_load_dwordx4 v[180:183], v[136:137], off offset:256
	global_load_dwordx4 v[176:179], v[138:139], off
	global_load_dwordx4 v[172:175], v[138:139], off offset:256
	global_load_dwordx4 v[168:171], v[140:141], off
	global_load_dwordx4 v[164:167], v[140:141], off offset:256
	global_load_dwordx4 v[160:163], v[142:143], off
	global_load_dwordx4 v[156:159], v[142:143], off offset:256
	global_load_dwordx4 v[152:155], v[144:145], off
	global_load_dwordx4 v[148:151], v[144:145], off offset:256
	s_nop 0
	global_load_dwordx4 v[142:145], v[248:249], off
	global_load_dwordx4 v[138:141], v[248:249], off offset:256
	global_load_dwordx4 v[134:137], v[128:129], off
	s_nop 0
	global_load_dwordx4 v[126:129], v[128:129], off offset:256
	s_lshl_b32 s18, s3, 2
	s_ashr_i32 s19, s18, 31
	s_waitcnt vmcnt(0)
	v_lshlrev_b32_e32 v248, 16, v240
	v_and_b32_e32 v249, 0xffff0000, v240
	v_lshlrev_b32_e32 v240, 16, v241
	v_and_b32_e32 v241, 0xffff0000, v241
	v_lshlrev_b32_e32 v252, 16, v242
	v_and_b32_e32 v253, 0xffff0000, v242
	v_lshlrev_b32_e32 v242, 16, v243
	v_and_b32_e32 v243, 0xffff0000, v243
	v_pk_fma_f32 v[132:133], v[132:133], 0.5, v[240:241] op_sel_hi:[1,0,1]
	v_pk_fma_f32 v[240:241], v[124:125], 0.5, v[242:243] op_sel_hi:[1,0,1]
	v_pk_fma_f32 v[124:125], v[122:123], 0.5, v[252:253] op_sel_hi:[1,0,1]
	v_pk_fma_f32 v[130:131], v[130:131], 0.5, v[248:249] op_sel_hi:[1,0,1]
	v_lshlrev_b32_e32 v236, 16, v244
	v_cvt_pk_bf16_f32 v122, v130, v131
	v_cvt_pk_bf16_f32 v123, v132, v133
	v_cvt_pk_bf16_f32 v124, v124, v125
	v_cvt_pk_bf16_f32 v125, v240, v241
	global_store_dwordx4 v[250:251], v[122:125], off
	v_lshlrev_b32_e32 v130, 16, v122
	v_lshlrev_b32_e32 v131, 16, v123
	v_and_b32_e32 v122, 0xffff0000, v122
	v_and_b32_e32 v123, 0xffff0000, v123
	v_lshlrev_b32_e32 v132, 16, v124
	v_and_b32_e32 v124, 0xffff0000, v124
	v_lshlrev_b32_e32 v133, 16, v125
	v_and_b32_e32 v125, 0xffff0000, v125
	v_mul_f32_e32 v122, v122, v122
	v_mul_f32_e32 v123, v123, v123
	v_mul_f32_e32 v124, v124, v124
	v_mul_f32_e32 v125, v125, v125
	v_fmac_f32_e32 v122, v130, v130
	v_fmac_f32_e32 v123, v131, v131
	v_fmac_f32_e32 v124, v132, v132
	v_fmac_f32_e32 v125, v133, v133
	v_add_f32_e32 v122, v122, v123
	v_add_f32_e32 v123, v124, v125
	v_and_b32_e32 v237, 0xffff0000, v244
	v_add_f32_e32 v132, v122, v123
	v_lshlrev_b32_e32 v122, 16, v245
	v_and_b32_e32 v123, 0xffff0000, v245
	v_lshlrev_b32_e32 v124, 16, v246
	v_and_b32_e32 v125, 0xffff0000, v246
	v_lshlrev_b32_e32 v130, 16, v247
	v_and_b32_e32 v131, 0xffff0000, v247
	v_pk_fma_f32 v[120:121], v[120:121], 0.5, v[122:123] op_sel_hi:[1,0,1]
	v_pk_fma_f32 v[118:119], v[118:119], 0.5, v[236:237] op_sel_hi:[1,0,1]
	v_pk_fma_f32 v[122:123], v[116:117], 0.5, v[130:131] op_sel_hi:[1,0,1]
	v_pk_fma_f32 v[116:117], v[114:115], 0.5, v[124:125] op_sel_hi:[1,0,1]
	v_cvt_pk_bf16_f32 v114, v118, v119
	v_cvt_pk_bf16_f32 v115, v120, v121
	s_nop 0
	v_cvt_pk_bf16_f32 v116, v116, v117
	v_cvt_pk_bf16_f32 v117, v122, v123
	global_store_dwordx4 v[250:251], v[114:117], off offset:256
	v_lshlrev_b32_e32 v118, 16, v114
	v_lshlrev_b32_e32 v119, 16, v115
	v_and_b32_e32 v114, 0xffff0000, v114
	v_and_b32_e32 v115, 0xffff0000, v115
	v_mul_f32_e32 v114, v114, v114
	v_mul_f32_e32 v115, v115, v115
	v_lshlrev_b32_e32 v120, 16, v116
	v_and_b32_e32 v116, 0xffff0000, v116
	v_lshlrev_b32_e32 v121, 16, v117
	v_and_b32_e32 v117, 0xffff0000, v117
	v_fmac_f32_e32 v114, v118, v118
	v_fmac_f32_e32 v115, v119, v119
	v_add_f32_e32 v114, v114, v115
	v_mul_f32_e32 v115, v116, v116
	v_mul_f32_e32 v116, v117, v117
	v_fmac_f32_e32 v115, v120, v120
	v_fmac_f32_e32 v116, v121, v121
	v_add_f32_e32 v115, v115, v116
	v_add_f32_e32 v114, v114, v115
	s_mov_b32 s2, 0
	v_add_f32_e32 v114, v132, v114
	v_mbcnt_lo_u32_b32 v115, -1, s2
	v_mbcnt_hi_u32_b32 v115, -1, v115
	v_lshlrev_b32_e32 v115, 2, v115
	v_xor_b32_e32 v115, 64, v115
	ds_bpermute_b32 v115, v115, v114
	s_mov_b32 s2, 0
	s_waitcnt lgkmcnt(0)
	v_add_f32_e32 v114, v114, v115
	v_mbcnt_lo_u32_b32 v115, -1, s2
	v_mbcnt_hi_u32_b32 v115, -1, v115
	v_lshlrev_b32_e32 v115, 2, v115
	v_xor_b32_e32 v115, 0x80, v115
	ds_bpermute_b32 v115, v115, v114
	s_and_saveexec_b64 s[20:21], s[6:7]
	s_cbranch_execz .LBB0_284
	v_lshlrev_b64 v[116:117], 7, v[224:225]
	v_lshl_add_u64 v[116:117], s[14:15], 0, v[116:117]
	v_lshl_add_u64 v[116:117], s[18:19], 2, v[116:117]
	s_lshl_b32 s50, s35, 2
	v_lshl_add_u64 v[116:117], v[116:117], 0, s[50:51]
	s_waitcnt lgkmcnt(0)
	v_add_f32_e32 v114, v114, v115
	global_store_dword v[116:117], v114, off

.LBB0_322:
	s_add_u32 s22, s20, 0x100
	s_addc_u32 s23, s21, 0
	s_add_i32 s2, 0, 0x10000
	s_cmpk_eq_i32 s42, 0x52
	s_cselect_b32 s27, s9, s23
	s_cselect_b32 s26, s8, s22
	s_cselect_b32 s25, s19, s41
	s_cselect_b32 s24, s18, s40
	s_add_u32 s100, s20, 0xffea8000
	s_addc_u32 s101, s21, -1
	s_add_i32 s43, 0, 0x14000
	v_add_u32_e32 v142, s2, v240
	v_add_u32_e32 v160, s43, v240
	s_mov_b32 m0, s35
	ds_read_b128 v[130:133], v142
	ds_read_b128 v[134:137], v142 offset:1024
	ds_read_b128 v[138:141], v142 offset:2048
	ds_read_b128 v[142:145], v142 offset:3072
	global_load_lds_dwordx4 v208, s[100:101]
	s_mov_b32 m0, s36
	ds_read_b128 v[148:151], v160
	ds_read_b128 v[152:155], v160 offset:1024
	ds_read_b128 v[156:159], v160 offset:2048
	ds_read_b128 v[160:163], v160 offset:3072
	global_load_lds_dwordx4 v210, s[100:101]
	s_add_i32 m0, s1, 0xc000
	ds_read_b128 v[164:167], v242
	ds_read_b128 v[168:171], v242 offset:1024
	ds_read_b128 v[172:175], v242 offset:2048
	ds_read_b128 v[176:179], v242 offset:3072
	global_load_lds_dwordx4 v208, s[20:21]
	s_add_i32 m0, s1, 0xe000
	ds_read_b128 v[180:183], v242 offset:4096
	ds_read_b128 v[184:187], v242 offset:5120
	ds_read_b128 v[188:191], v242 offset:6144
	ds_read_b128 v[212:215], v242 offset:7168
	global_load_lds_dwordx4 v210, s[20:21]
	s_waitcnt vmcnt(8)
	s_waitcnt lgkmcnt(0)
	s_barrier
	s_waitcnt lgkmcnt(0)
	v_mfma_f32_16x16x32_bf16 v[126:129], v[130:133], v[164:167], v[126:129]
	v_mfma_f32_16x16x32_bf16 v[122:125], v[138:141], v[164:167], v[122:125]
	v_mfma_f32_16x16x32_bf16 v[110:113], v[130:133], v[172:175], v[110:113]
	v_mfma_f32_16x16x32_bf16 v[106:109], v[138:141], v[172:175], v[106:109]
	v_mfma_f32_16x16x32_bf16 v[94:97], v[130:133], v[180:183], v[94:97]
	v_mfma_f32_16x16x32_bf16 v[90:93], v[138:141], v[180:183], v[90:93]
	v_mfma_f32_16x16x32_bf16 v[78:81], v[130:133], v[188:191], v[78:81]
	v_mfma_f32_16x16x32_bf16 v[74:77], v[138:141], v[188:191], v[74:77]
	v_mfma_f32_16x16x32_bf16 v[126:129], v[134:137], v[168:171], v[126:129]
	v_mfma_f32_16x16x32_bf16 v[122:125], v[142:145], v[168:171], v[122:125]
	v_mfma_f32_16x16x32_bf16 v[110:113], v[134:137], v[176:179], v[110:113]
	v_mfma_f32_16x16x32_bf16 v[106:109], v[142:145], v[176:179], v[106:109]
	v_mfma_f32_16x16x32_bf16 v[94:97], v[134:137], v[184:187], v[94:97]
	v_mfma_f32_16x16x32_bf16 v[90:93], v[142:145], v[184:187], v[90:93]
	v_mfma_f32_16x16x32_bf16 v[78:81], v[134:137], v[212:215], v[78:81]
	v_mfma_f32_16x16x32_bf16 v[74:77], v[142:145], v[212:215], v[74:77]
	v_mfma_f32_16x16x32_bf16 v[118:121], v[148:151], v[164:167], v[118:121]
	v_mfma_f32_16x16x32_bf16 v[114:117], v[156:159], v[164:167], v[114:117]
	v_mfma_f32_16x16x32_bf16 v[102:105], v[148:151], v[172:175], v[102:105]
	v_mfma_f32_16x16x32_bf16 v[98:101], v[156:159], v[172:175], v[98:101]
	v_mfma_f32_16x16x32_bf16 v[86:89], v[148:151], v[180:183], v[86:89]
	v_mfma_f32_16x16x32_bf16 v[82:85], v[156:159], v[180:183], v[82:85]
	v_mfma_f32_16x16x32_bf16 v[70:73], v[148:151], v[188:191], v[70:73]
	v_mfma_f32_16x16x32_bf16 v[66:69], v[156:159], v[188:191], v[66:69]
	v_mfma_f32_16x16x32_bf16 v[118:121], v[152:155], v[168:171], v[118:121]
	v_mfma_f32_16x16x32_bf16 v[114:117], v[160:163], v[168:171], v[114:117]
	v_mfma_f32_16x16x32_bf16 v[102:105], v[152:155], v[176:179], v[102:105]
	v_mfma_f32_16x16x32_bf16 v[98:101], v[160:163], v[176:179], v[98:101]
	v_mfma_f32_16x16x32_bf16 v[86:89], v[152:155], v[184:187], v[86:89]
	v_mfma_f32_16x16x32_bf16 v[82:85], v[160:163], v[184:187], v[82:85]
	s_barrier
	v_mfma_f32_16x16x32_bf16 v[70:73], v[152:155], v[212:215], v[70:73]
	v_mfma_f32_16x16x32_bf16 v[66:69], v[160:163], v[212:215], v[66:69]
	s_add_u32 s20, s24, 0x158000
	s_addc_u32 s21, s25, 0
	s_add_i32 s2, s2, s0
	s_mov_b32 m0, s2
	ds_read_b128 v[164:167], v242 offset:16384
	ds_read_b128 v[168:171], v242 offset:17408
	global_load_lds_dwordx4 v0, s[24:25]
	s_add_i32 m0, s2, 0x2000
	s_add_i32 s2, s43, s0
	ds_read_b128 v[172:175], v242 offset:18432
	ds_read_b128 v[176:179], v242 offset:19456
	global_load_lds_dwordx4 v192, s[24:25]
	s_mov_b32 m0, s2
	ds_read_b128 v[180:183], v242 offset:20480
	ds_read_b128 v[184:187], v242 offset:21504
	global_load_lds_dwordx4 v0, s[20:21]
	s_add_i32 m0, s2, 0x2000
	ds_read_b128 v[188:191], v242 offset:22528
	ds_read_b128 v[212:215], v242 offset:23552
	global_load_lds_dwordx4 v192, s[20:21]
	s_waitcnt vmcnt(6)
	s_waitcnt lgkmcnt(0)
	s_barrier
	s_waitcnt lgkmcnt(0)
	v_mfma_f32_16x16x32_bf16 v[62:65], v[130:133], v[164:167], v[62:65]
	v_mfma_f32_16x16x32_bf16 v[58:61], v[138:141], v[164:167], v[58:61]
	v_mfma_f32_16x16x32_bf16 v[46:49], v[130:133], v[172:175], v[46:49]
	v_mfma_f32_16x16x32_bf16 v[42:45], v[138:141], v[172:175], v[42:45]
	v_mfma_f32_16x16x32_bf16 v[30:33], v[130:133], v[180:183], v[30:33]
	v_mfma_f32_16x16x32_bf16 v[26:29], v[138:141], v[180:183], v[26:29]
	v_mfma_f32_16x16x32_bf16 v[14:17], v[130:133], v[188:191], v[14:17]
	v_mfma_f32_16x16x32_bf16 v[10:13], v[138:141], v[188:191], v[10:13]
	v_mfma_f32_16x16x32_bf16 v[62:65], v[134:137], v[168:171], v[62:65]
	v_mfma_f32_16x16x32_bf16 v[58:61], v[142:145], v[168:171], v[58:61]
	v_mfma_f32_16x16x32_bf16 v[46:49], v[134:137], v[176:179], v[46:49]
	v_mfma_f32_16x16x32_bf16 v[42:45], v[142:145], v[176:179], v[42:45]
	v_mfma_f32_16x16x32_bf16 v[30:33], v[134:137], v[184:187], v[30:33]
	v_mfma_f32_16x16x32_bf16 v[26:29], v[142:145], v[184:187], v[26:29]
	v_mfma_f32_16x16x32_bf16 v[14:17], v[134:137], v[212:215], v[14:17]
	v_mfma_f32_16x16x32_bf16 v[10:13], v[142:145], v[212:215], v[10:13]
	v_mfma_f32_16x16x32_bf16 v[54:57], v[148:151], v[164:167], v[54:57]
	v_mfma_f32_16x16x32_bf16 v[50:53], v[156:159], v[164:167], v[50:53]
	v_mfma_f32_16x16x32_bf16 v[38:41], v[148:151], v[172:175], v[38:41]
	v_mfma_f32_16x16x32_bf16 v[34:37], v[156:159], v[172:175], v[34:37]
	v_mfma_f32_16x16x32_bf16 v[22:25], v[148:151], v[180:183], v[22:25]
	v_mfma_f32_16x16x32_bf16 v[18:21], v[156:159], v[180:183], v[18:21]
	v_mfma_f32_16x16x32_bf16 v[6:9], v[148:151], v[188:191], v[6:9]
	v_mfma_f32_16x16x32_bf16 v[2:5], v[156:159], v[188:191], v[2:5]
	v_mfma_f32_16x16x32_bf16 v[54:57], v[152:155], v[168:171], v[54:57]
	v_mfma_f32_16x16x32_bf16 v[50:53], v[160:163], v[168:171], v[50:53]
	v_mfma_f32_16x16x32_bf16 v[38:41], v[152:155], v[176:179], v[38:41]
	v_mfma_f32_16x16x32_bf16 v[34:37], v[160:163], v[176:179], v[34:37]
	v_mfma_f32_16x16x32_bf16 v[22:25], v[152:155], v[184:187], v[22:25]
	v_mfma_f32_16x16x32_bf16 v[18:21], v[160:163], v[184:187], v[18:21]
	s_barrier
	v_mfma_f32_16x16x32_bf16 v[6:9], v[152:155], v[212:215], v[6:9]
	v_mfma_f32_16x16x32_bf16 v[2:5], v[160:163], v[212:215], v[2:5]
	s_add_u32 s20, s26, 0x158000
	s_addc_u32 s21, s27, 0
	s_add_i32 s2, 0, 0x18000
	s_add_i32 s43, 0, 0x1c000
	v_add_u32_e32 v142, s2, v240
	v_add_u32_e32 v160, s43, v240
	s_mov_b32 m0, s1
	ds_read_b128 v[130:133], v142
	ds_read_b128 v[134:137], v142 offset:1024
	ds_read_b128 v[138:141], v142 offset:2048
	ds_read_b128 v[142:145], v142 offset:3072
	global_load_lds_dwordx4 v206, s[26:27]
	s_mov_b32 m0, s30
	ds_read_b128 v[148:151], v160
	ds_read_b128 v[152:155], v160 offset:1024
	ds_read_b128 v[156:159], v160 offset:2048
	ds_read_b128 v[160:163], v160 offset:3072
	global_load_lds_dwordx4 v194, s[26:27]
	s_mov_b32 m0, s31
	ds_read_b128 v[164:167], v242 offset:32768
	ds_read_b128 v[168:171], v242 offset:33792
	ds_read_b128 v[172:175], v242 offset:34816
	ds_read_b128 v[176:179], v242 offset:35840
	global_load_lds_dwordx4 v206, s[20:21]
	s_mov_b32 m0, s33
	ds_read_b128 v[180:183], v242 offset:36864
	ds_read_b128 v[184:187], v242 offset:37888
	ds_read_b128 v[188:191], v242 offset:38912
	ds_read_b128 v[212:215], v242 offset:39936
	global_load_lds_dwordx4 v194, s[20:21]
	s_waitcnt vmcnt(8)
	s_waitcnt lgkmcnt(0)
	s_barrier
	s_waitcnt lgkmcnt(0)
	v_mfma_f32_16x16x32_bf16 v[126:129], v[130:133], v[164:167], v[126:129]
	v_mfma_f32_16x16x32_bf16 v[122:125], v[138:141], v[164:167], v[122:125]
	v_mfma_f32_16x16x32_bf16 v[110:113], v[130:133], v[172:175], v[110:113]
	v_mfma_f32_16x16x32_bf16 v[106:109], v[138:141], v[172:175], v[106:109]
	v_mfma_f32_16x16x32_bf16 v[94:97], v[130:133], v[180:183], v[94:97]
	v_mfma_f32_16x16x32_bf16 v[90:93], v[138:141], v[180:183], v[90:93]
	v_mfma_f32_16x16x32_bf16 v[78:81], v[130:133], v[188:191], v[78:81]
	v_mfma_f32_16x16x32_bf16 v[74:77], v[138:141], v[188:191], v[74:77]
	v_mfma_f32_16x16x32_bf16 v[126:129], v[134:137], v[168:171], v[126:129]
	v_mfma_f32_16x16x32_bf16 v[122:125], v[142:145], v[168:171], v[122:125]
	v_mfma_f32_16x16x32_bf16 v[110:113], v[134:137], v[176:179], v[110:113]
	v_mfma_f32_16x16x32_bf16 v[106:109], v[142:145], v[176:179], v[106:109]
	v_mfma_f32_16x16x32_bf16 v[94:97], v[134:137], v[184:187], v[94:97]
	v_mfma_f32_16x16x32_bf16 v[90:93], v[142:145], v[184:187], v[90:93]
	v_mfma_f32_16x16x32_bf16 v[78:81], v[134:137], v[212:215], v[78:81]
	v_mfma_f32_16x16x32_bf16 v[74:77], v[142:145], v[212:215], v[74:77]
	v_mfma_f32_16x16x32_bf16 v[118:121], v[148:151], v[164:167], v[118:121]
	v_mfma_f32_16x16x32_bf16 v[114:117], v[156:159], v[164:167], v[114:117]
	v_mfma_f32_16x16x32_bf16 v[102:105], v[148:151], v[172:175], v[102:105]
	v_mfma_f32_16x16x32_bf16 v[98:101], v[156:159], v[172:175], v[98:101]
	v_mfma_f32_16x16x32_bf16 v[86:89], v[148:151], v[180:183], v[86:89]
	v_mfma_f32_16x16x32_bf16 v[82:85], v[156:159], v[180:183], v[82:85]
	v_mfma_f32_16x16x32_bf16 v[70:73], v[148:151], v[188:191], v[70:73]
	v_mfma_f32_16x16x32_bf16 v[66:69], v[156:159], v[188:191], v[66:69]
	v_mfma_f32_16x16x32_bf16 v[118:121], v[152:155], v[168:171], v[118:121]
	v_mfma_f32_16x16x32_bf16 v[114:117], v[160:163], v[168:171], v[114:117]
	v_mfma_f32_16x16x32_bf16 v[102:105], v[152:155], v[176:179], v[102:105]
	v_mfma_f32_16x16x32_bf16 v[98:101], v[160:163], v[176:179], v[98:101]
	v_mfma_f32_16x16x32_bf16 v[86:89], v[152:155], v[184:187], v[86:89]
	v_mfma_f32_16x16x32_bf16 v[82:85], v[160:163], v[184:187], v[82:85]
	s_barrier
	v_mfma_f32_16x16x32_bf16 v[70:73], v[152:155], v[212:215], v[70:73]
	v_mfma_f32_16x16x32_bf16 v[66:69], v[160:163], v[212:215], v[66:69]
	s_add_u32 s20, s24, 0x158080
	s_addc_u32 s21, s25, 0
	s_add_u32 s24, s24, 0x80
	s_addc_u32 s25, s25, 0
	s_add_i32 s2, s2, s0
	s_mov_b32 m0, s2
	ds_read_b128 v[164:167], v242 offset:49152
	ds_read_b128 v[168:171], v242 offset:50176
	global_load_lds_dwordx4 v0, s[24:25]
	s_add_i32 m0, s2, 0x2000
	s_add_i32 s2, s43, s0
	ds_read_b128 v[172:175], v242 offset:51200
	ds_read_b128 v[176:179], v242 offset:52224
	global_load_lds_dwordx4 v192, s[24:25]
	s_mov_b32 m0, s2
	ds_read_b128 v[180:183], v242 offset:53248
	ds_read_b128 v[184:187], v242 offset:54272
	global_load_lds_dwordx4 v0, s[20:21]
	s_add_i32 m0, s2, 0x2000
	ds_read_b128 v[188:191], v242 offset:55296
	ds_read_b128 v[212:215], v242 offset:56320
	global_load_lds_dwordx4 v192, s[20:21]
	s_waitcnt vmcnt(6)
	s_waitcnt lgkmcnt(0)
	s_barrier
	s_waitcnt lgkmcnt(0)
	v_mfma_f32_16x16x32_bf16 v[62:65], v[130:133], v[164:167], v[62:65]
	v_mfma_f32_16x16x32_bf16 v[58:61], v[138:141], v[164:167], v[58:61]
	v_mfma_f32_16x16x32_bf16 v[46:49], v[130:133], v[172:175], v[46:49]
	v_mfma_f32_16x16x32_bf16 v[42:45], v[138:141], v[172:175], v[42:45]
	v_mfma_f32_16x16x32_bf16 v[30:33], v[130:133], v[180:183], v[30:33]
	v_mfma_f32_16x16x32_bf16 v[26:29], v[138:141], v[180:183], v[26:29]
	v_mfma_f32_16x16x32_bf16 v[14:17], v[130:133], v[188:191], v[14:17]
	v_mfma_f32_16x16x32_bf16 v[10:13], v[138:141], v[188:191], v[10:13]
	v_mfma_f32_16x16x32_bf16 v[62:65], v[134:137], v[168:171], v[62:65]
	v_mfma_f32_16x16x32_bf16 v[58:61], v[142:145], v[168:171], v[58:61]
	v_mfma_f32_16x16x32_bf16 v[46:49], v[134:137], v[176:179], v[46:49]
	v_mfma_f32_16x16x32_bf16 v[42:45], v[142:145], v[176:179], v[42:45]
	v_mfma_f32_16x16x32_bf16 v[30:33], v[134:137], v[184:187], v[30:33]
	v_mfma_f32_16x16x32_bf16 v[26:29], v[142:145], v[184:187], v[26:29]
	v_mfma_f32_16x16x32_bf16 v[14:17], v[134:137], v[212:215], v[14:17]
	v_mfma_f32_16x16x32_bf16 v[10:13], v[142:145], v[212:215], v[10:13]
	v_mfma_f32_16x16x32_bf16 v[54:57], v[148:151], v[164:167], v[54:57]
	v_mfma_f32_16x16x32_bf16 v[50:53], v[156:159], v[164:167], v[50:53]
	v_mfma_f32_16x16x32_bf16 v[38:41], v[148:151], v[172:175], v[38:41]
	v_mfma_f32_16x16x32_bf16 v[34:37], v[156:159], v[172:175], v[34:37]
	v_mfma_f32_16x16x32_bf16 v[22:25], v[148:151], v[180:183], v[22:25]
	v_mfma_f32_16x16x32_bf16 v[18:21], v[156:159], v[180:183], v[18:21]
	v_mfma_f32_16x16x32_bf16 v[6:9], v[148:151], v[188:191], v[6:9]
	v_mfma_f32_16x16x32_bf16 v[2:5], v[156:159], v[188:191], v[2:5]
	v_mfma_f32_16x16x32_bf16 v[54:57], v[152:155], v[168:171], v[54:57]
	v_mfma_f32_16x16x32_bf16 v[50:53], v[160:163], v[168:171], v[50:53]
	v_mfma_f32_16x16x32_bf16 v[38:41], v[152:155], v[176:179], v[38:41]
	v_mfma_f32_16x16x32_bf16 v[34:37], v[160:163], v[176:179], v[34:37]
	v_mfma_f32_16x16x32_bf16 v[22:25], v[152:155], v[184:187], v[22:25]
	v_mfma_f32_16x16x32_bf16 v[18:21], v[160:163], v[184:187], v[18:21]
	s_barrier
	v_mfma_f32_16x16x32_bf16 v[6:9], v[152:155], v[212:215], v[6:9]
	v_mfma_f32_16x16x32_bf16 v[2:5], v[160:163], v[212:215], v[2:5]
	s_add_i32 s42, s42, 2
	s_add_u32 s40, s40, 0x100
	s_addc_u32 s41, s41, 0
	s_cmpk_gt_u32 s42, 0x53
	s_mov_b64 s[20:21], s[22:23]
	s_cbranch_scc0 .LBB0_322
	s_nop 0
	s_nop 0
	s_nop 0
	s_and_b64 vcc, exec, s[16:17]
	s_cbranch_vccz .LBB0_325
	s_barrier

.LBB0_408:
	s_add_u32 s2, s24, 0xfff80080
	s_addc_u32 s22, s25, -1
	s_add_i32 s45, 0, 0x10000
	s_cmp_eq_u32 s44, 28
	s_cselect_b32 s27, s17, s22
	s_cselect_b32 s26, s40, s2
	v_add_u32_e32 v144, s45, v148
	s_cselect_b32 s23, s15, s43
	s_cselect_b32 s22, s41, s42
	s_add_u32 s100, s24, 0xfff80000
	s_addc_u32 s101, s25, -1
	s_add_i32 s2, 0, 0x14000
	s_mov_b32 m0, s35
	ds_read_b128 v[140:143], v144
	ds_read_b128 v[152:155], v144 offset:1024
	ds_read_b128 v[156:159], v144 offset:2048
	ds_read_b128 v[160:163], v144 offset:3072
	global_load_lds_dwordx4 v136, s[100:101]
	s_mov_b32 m0, s36
	v_add_u32_e32 v144, s2, v148
	ds_read_b128 v[164:167], v144
	ds_read_b128 v[168:171], v144 offset:1024
	ds_read_b128 v[172:175], v144 offset:2048
	ds_read_b128 v[176:179], v144 offset:3072
	global_load_lds_dwordx4 v138, s[100:101]
	s_add_i32 m0, s29, 0xc000
	ds_read_b128 v[180:183], v151
	ds_read_b128 v[184:187], v151 offset:1024
	ds_read_b128 v[188:191], v151 offset:2048
	ds_read_b128 v[192:195], v151 offset:3072
	global_load_lds_dwordx4 v136, s[24:25]
	s_add_i32 m0, s29, 0xe000
	ds_read_b128 v[206:209], v151 offset:4096
	ds_read_b128 v[210:213], v151 offset:5120
	ds_read_b128 v[214:217], v151 offset:6144
	ds_read_b128 v[218:221], v151 offset:7168
	global_load_lds_dwordx4 v138, s[24:25]
	s_waitcnt vmcnt(8)
	s_waitcnt lgkmcnt(0)
	s_barrier
	s_waitcnt lgkmcnt(0)
	v_mfma_f32_16x16x32_bf16 v[126:129], v[140:143], v[180:183], v[126:129]
	v_mfma_f32_16x16x32_bf16 v[122:125], v[156:159], v[180:183], v[122:125]
	v_mfma_f32_16x16x32_bf16 v[110:113], v[140:143], v[188:191], v[110:113]
	v_mfma_f32_16x16x32_bf16 v[106:109], v[156:159], v[188:191], v[106:109]
	v_mfma_f32_16x16x32_bf16 v[94:97], v[140:143], v[206:209], v[94:97]
	v_mfma_f32_16x16x32_bf16 v[90:93], v[156:159], v[206:209], v[90:93]
	v_mfma_f32_16x16x32_bf16 v[78:81], v[140:143], v[214:217], v[78:81]
	v_mfma_f32_16x16x32_bf16 v[74:77], v[156:159], v[214:217], v[74:77]
	v_mfma_f32_16x16x32_bf16 v[126:129], v[152:155], v[184:187], v[126:129]
	v_mfma_f32_16x16x32_bf16 v[122:125], v[160:163], v[184:187], v[122:125]
	v_mfma_f32_16x16x32_bf16 v[110:113], v[152:155], v[192:195], v[110:113]
	v_mfma_f32_16x16x32_bf16 v[106:109], v[160:163], v[192:195], v[106:109]
	v_mfma_f32_16x16x32_bf16 v[94:97], v[152:155], v[210:213], v[94:97]
	v_mfma_f32_16x16x32_bf16 v[90:93], v[160:163], v[210:213], v[90:93]
	v_mfma_f32_16x16x32_bf16 v[78:81], v[152:155], v[218:221], v[78:81]
	v_mfma_f32_16x16x32_bf16 v[74:77], v[160:163], v[218:221], v[74:77]
	v_mfma_f32_16x16x32_bf16 v[118:121], v[164:167], v[180:183], v[118:121]
	v_mfma_f32_16x16x32_bf16 v[114:117], v[172:175], v[180:183], v[114:117]
	v_mfma_f32_16x16x32_bf16 v[102:105], v[164:167], v[188:191], v[102:105]
	v_mfma_f32_16x16x32_bf16 v[98:101], v[172:175], v[188:191], v[98:101]
	v_mfma_f32_16x16x32_bf16 v[86:89], v[164:167], v[206:209], v[86:89]
	v_mfma_f32_16x16x32_bf16 v[82:85], v[172:175], v[206:209], v[82:85]
	v_mfma_f32_16x16x32_bf16 v[70:73], v[164:167], v[214:217], v[70:73]
	v_mfma_f32_16x16x32_bf16 v[66:69], v[172:175], v[214:217], v[66:69]
	v_mfma_f32_16x16x32_bf16 v[118:121], v[168:171], v[184:187], v[118:121]
	v_mfma_f32_16x16x32_bf16 v[114:117], v[176:179], v[184:187], v[114:117]
	v_mfma_f32_16x16x32_bf16 v[102:105], v[168:171], v[192:195], v[102:105]
	v_mfma_f32_16x16x32_bf16 v[98:101], v[176:179], v[192:195], v[98:101]
	v_mfma_f32_16x16x32_bf16 v[86:89], v[168:171], v[210:213], v[86:89]
	v_mfma_f32_16x16x32_bf16 v[82:85], v[176:179], v[210:213], v[82:85]
	s_barrier
	v_mfma_f32_16x16x32_bf16 v[70:73], v[168:171], v[218:221], v[70:73]
	v_mfma_f32_16x16x32_bf16 v[66:69], v[176:179], v[218:221], v[66:69]
	s_add_u32 s46, s22, 0x80000
	s_addc_u32 s47, s23, 0
	s_add_i32 s45, s45, s28
	s_mov_b32 m0, s45
	ds_read_b128 v[180:183], v151 offset:16384
	ds_read_b128 v[184:187], v151 offset:17408
	global_load_lds_dwordx4 v0, s[22:23]
	s_add_i32 m0, s45, 0x2000
	s_add_i32 s2, s2, s28
	ds_read_b128 v[188:191], v151 offset:18432
	ds_read_b128 v[192:195], v151 offset:19456
	global_load_lds_dwordx4 v130, s[22:23]
	s_mov_b32 m0, s2
	ds_read_b128 v[206:209], v151 offset:20480
	ds_read_b128 v[210:213], v151 offset:21504
	global_load_lds_dwordx4 v0, s[46:47]
	s_add_i32 m0, s2, 0x2000
	ds_read_b128 v[214:217], v151 offset:22528
	ds_read_b128 v[218:221], v151 offset:23552
	global_load_lds_dwordx4 v130, s[46:47]
	s_waitcnt vmcnt(6)
	s_waitcnt lgkmcnt(0)
	s_barrier
	s_waitcnt lgkmcnt(0)
	v_mfma_f32_16x16x32_bf16 v[62:65], v[140:143], v[180:183], v[62:65]
	v_mfma_f32_16x16x32_bf16 v[58:61], v[156:159], v[180:183], v[58:61]
	v_mfma_f32_16x16x32_bf16 v[46:49], v[140:143], v[188:191], v[46:49]
	v_mfma_f32_16x16x32_bf16 v[42:45], v[156:159], v[188:191], v[42:45]
	v_mfma_f32_16x16x32_bf16 v[30:33], v[140:143], v[206:209], v[30:33]
	v_mfma_f32_16x16x32_bf16 v[26:29], v[156:159], v[206:209], v[26:29]
	v_mfma_f32_16x16x32_bf16 v[14:17], v[140:143], v[214:217], v[14:17]
	v_mfma_f32_16x16x32_bf16 v[10:13], v[156:159], v[214:217], v[10:13]
	v_mfma_f32_16x16x32_bf16 v[62:65], v[152:155], v[184:187], v[62:65]
	v_mfma_f32_16x16x32_bf16 v[58:61], v[160:163], v[184:187], v[58:61]
	v_mfma_f32_16x16x32_bf16 v[46:49], v[152:155], v[192:195], v[46:49]
	v_mfma_f32_16x16x32_bf16 v[42:45], v[160:163], v[192:195], v[42:45]
	v_mfma_f32_16x16x32_bf16 v[30:33], v[152:155], v[210:213], v[30:33]
	v_mfma_f32_16x16x32_bf16 v[26:29], v[160:163], v[210:213], v[26:29]
	v_mfma_f32_16x16x32_bf16 v[14:17], v[152:155], v[218:221], v[14:17]
	v_mfma_f32_16x16x32_bf16 v[10:13], v[160:163], v[218:221], v[10:13]
	v_mfma_f32_16x16x32_bf16 v[54:57], v[164:167], v[180:183], v[54:57]
	v_mfma_f32_16x16x32_bf16 v[50:53], v[172:175], v[180:183], v[50:53]
	v_mfma_f32_16x16x32_bf16 v[38:41], v[164:167], v[188:191], v[38:41]
	v_mfma_f32_16x16x32_bf16 v[34:37], v[172:175], v[188:191], v[34:37]
	v_mfma_f32_16x16x32_bf16 v[22:25], v[164:167], v[206:209], v[22:25]
	v_mfma_f32_16x16x32_bf16 v[18:21], v[172:175], v[206:209], v[18:21]
	v_mfma_f32_16x16x32_bf16 v[6:9], v[164:167], v[214:217], v[6:9]
	v_mfma_f32_16x16x32_bf16 v[2:5], v[172:175], v[214:217], v[2:5]
	v_mfma_f32_16x16x32_bf16 v[54:57], v[168:171], v[184:187], v[54:57]
	v_mfma_f32_16x16x32_bf16 v[50:53], v[176:179], v[184:187], v[50:53]
	v_mfma_f32_16x16x32_bf16 v[38:41], v[168:171], v[192:195], v[38:41]
	v_mfma_f32_16x16x32_bf16 v[34:37], v[176:179], v[192:195], v[34:37]
	v_mfma_f32_16x16x32_bf16 v[22:25], v[168:171], v[210:213], v[22:25]
	v_mfma_f32_16x16x32_bf16 v[18:21], v[176:179], v[210:213], v[18:21]
	s_barrier
	v_mfma_f32_16x16x32_bf16 v[6:9], v[168:171], v[218:221], v[6:9]
	v_mfma_f32_16x16x32_bf16 v[2:5], v[176:179], v[218:221], v[2:5]
	s_add_u32 s26, s26, 0x80000
	s_addc_u32 s27, s27, 0
	s_add_u32 s100, s26, 0xfff80000
	s_addc_u32 s101, s27, -1
	s_add_i32 s2, 0, 0x18000
	s_add_i32 s45, 0, 0x1c000
	v_add_u32_e32 v160, s2, v148
	v_add_u32_e32 v176, s45, v148
	s_mov_b32 m0, s29
	ds_read_b128 v[140:143], v160
	ds_read_b128 v[152:155], v160 offset:1024
	ds_read_b128 v[156:159], v160 offset:2048
	ds_read_b128 v[160:163], v160 offset:3072
	global_load_lds_dwordx4 v134, s[100:101]
	s_mov_b32 m0, s30
	ds_read_b128 v[164:167], v176
	ds_read_b128 v[168:171], v176 offset:1024
	ds_read_b128 v[172:175], v176 offset:2048
	ds_read_b128 v[176:179], v176 offset:3072
	global_load_lds_dwordx4 v132, s[100:101]
	s_mov_b32 m0, s31
	ds_read_b128 v[180:183], v151 offset:32768
	ds_read_b128 v[184:187], v151 offset:33792
	ds_read_b128 v[188:191], v151 offset:34816
	ds_read_b128 v[192:195], v151 offset:35840
	global_load_lds_dwordx4 v134, s[26:27]
	s_mov_b32 m0, s33
	ds_read_b128 v[206:209], v151 offset:36864
	ds_read_b128 v[210:213], v151 offset:37888
	ds_read_b128 v[214:217], v151 offset:38912
	ds_read_b128 v[218:221], v151 offset:39936
	global_load_lds_dwordx4 v132, s[26:27]
	s_waitcnt vmcnt(8)
	s_waitcnt lgkmcnt(0)
	s_barrier
	s_waitcnt lgkmcnt(0)
	v_mfma_f32_16x16x32_bf16 v[126:129], v[140:143], v[180:183], v[126:129]
	v_mfma_f32_16x16x32_bf16 v[122:125], v[156:159], v[180:183], v[122:125]
	v_mfma_f32_16x16x32_bf16 v[110:113], v[140:143], v[188:191], v[110:113]
	v_mfma_f32_16x16x32_bf16 v[106:109], v[156:159], v[188:191], v[106:109]
	v_mfma_f32_16x16x32_bf16 v[94:97], v[140:143], v[206:209], v[94:97]
	v_mfma_f32_16x16x32_bf16 v[90:93], v[156:159], v[206:209], v[90:93]
	v_mfma_f32_16x16x32_bf16 v[78:81], v[140:143], v[214:217], v[78:81]
	v_mfma_f32_16x16x32_bf16 v[74:77], v[156:159], v[214:217], v[74:77]
	v_mfma_f32_16x16x32_bf16 v[126:129], v[152:155], v[184:187], v[126:129]
	v_mfma_f32_16x16x32_bf16 v[122:125], v[160:163], v[184:187], v[122:125]
	v_mfma_f32_16x16x32_bf16 v[110:113], v[152:155], v[192:195], v[110:113]
	v_mfma_f32_16x16x32_bf16 v[106:109], v[160:163], v[192:195], v[106:109]
	v_mfma_f32_16x16x32_bf16 v[94:97], v[152:155], v[210:213], v[94:97]
	v_mfma_f32_16x16x32_bf16 v[90:93], v[160:163], v[210:213], v[90:93]
	v_mfma_f32_16x16x32_bf16 v[78:81], v[152:155], v[218:221], v[78:81]
	v_mfma_f32_16x16x32_bf16 v[74:77], v[160:163], v[218:221], v[74:77]
	v_mfma_f32_16x16x32_bf16 v[118:121], v[164:167], v[180:183], v[118:121]
	v_mfma_f32_16x16x32_bf16 v[114:117], v[172:175], v[180:183], v[114:117]
	v_mfma_f32_16x16x32_bf16 v[102:105], v[164:167], v[188:191], v[102:105]
	v_mfma_f32_16x16x32_bf16 v[98:101], v[172:175], v[188:191], v[98:101]
	v_mfma_f32_16x16x32_bf16 v[86:89], v[164:167], v[206:209], v[86:89]
	v_mfma_f32_16x16x32_bf16 v[82:85], v[172:175], v[206:209], v[82:85]
	v_mfma_f32_16x16x32_bf16 v[70:73], v[164:167], v[214:217], v[70:73]
	v_mfma_f32_16x16x32_bf16 v[66:69], v[172:175], v[214:217], v[66:69]
	v_mfma_f32_16x16x32_bf16 v[118:121], v[168:171], v[184:187], v[118:121]
	v_mfma_f32_16x16x32_bf16 v[114:117], v[176:179], v[184:187], v[114:117]
	v_mfma_f32_16x16x32_bf16 v[102:105], v[168:171], v[192:195], v[102:105]
	v_mfma_f32_16x16x32_bf16 v[98:101], v[176:179], v[192:195], v[98:101]
	v_mfma_f32_16x16x32_bf16 v[86:89], v[168:171], v[210:213], v[86:89]
	v_mfma_f32_16x16x32_bf16 v[82:85], v[176:179], v[210:213], v[82:85]
	s_barrier
	v_mfma_f32_16x16x32_bf16 v[70:73], v[168:171], v[218:221], v[70:73]
	v_mfma_f32_16x16x32_bf16 v[66:69], v[176:179], v[218:221], v[66:69]
	s_add_u32 s22, s22, 0x80080
	s_addc_u32 s23, s23, 0
	s_add_u32 s46, s46, 0xfff80080
	s_addc_u32 s47, s47, -1
	s_add_i32 s2, s2, s28
	s_mov_b32 m0, s2
	ds_read_b128 v[180:183], v151 offset:49152
	ds_read_b128 v[184:187], v151 offset:50176
	global_load_lds_dwordx4 v0, s[46:47]
	s_add_i32 m0, s2, 0x2000
	s_add_i32 s2, s45, s28
	ds_read_b128 v[188:191], v151 offset:51200
	ds_read_b128 v[192:195], v151 offset:52224
	global_load_lds_dwordx4 v130, s[46:47]
	s_mov_b32 m0, s2
	ds_read_b128 v[206:209], v151 offset:53248
	ds_read_b128 v[210:213], v151 offset:54272
	global_load_lds_dwordx4 v0, s[22:23]
	s_add_i32 m0, s2, 0x2000
	ds_read_b128 v[214:217], v151 offset:55296
	ds_read_b128 v[218:221], v151 offset:56320
	global_load_lds_dwordx4 v130, s[22:23]
	s_waitcnt vmcnt(6)
	s_waitcnt lgkmcnt(0)
	s_barrier
	s_waitcnt lgkmcnt(0)
	v_mfma_f32_16x16x32_bf16 v[62:65], v[140:143], v[180:183], v[62:65]
	v_mfma_f32_16x16x32_bf16 v[58:61], v[156:159], v[180:183], v[58:61]
	v_mfma_f32_16x16x32_bf16 v[46:49], v[140:143], v[188:191], v[46:49]
	v_mfma_f32_16x16x32_bf16 v[42:45], v[156:159], v[188:191], v[42:45]
	v_mfma_f32_16x16x32_bf16 v[30:33], v[140:143], v[206:209], v[30:33]
	v_mfma_f32_16x16x32_bf16 v[26:29], v[156:159], v[206:209], v[26:29]
	v_mfma_f32_16x16x32_bf16 v[14:17], v[140:143], v[214:217], v[14:17]
	v_mfma_f32_16x16x32_bf16 v[10:13], v[156:159], v[214:217], v[10:13]
	v_mfma_f32_16x16x32_bf16 v[62:65], v[152:155], v[184:187], v[62:65]
	v_mfma_f32_16x16x32_bf16 v[58:61], v[160:163], v[184:187], v[58:61]
	v_mfma_f32_16x16x32_bf16 v[46:49], v[152:155], v[192:195], v[46:49]
	v_mfma_f32_16x16x32_bf16 v[42:45], v[160:163], v[192:195], v[42:45]
	v_mfma_f32_16x16x32_bf16 v[30:33], v[152:155], v[210:213], v[30:33]
	v_mfma_f32_16x16x32_bf16 v[26:29], v[160:163], v[210:213], v[26:29]
	v_mfma_f32_16x16x32_bf16 v[14:17], v[152:155], v[218:221], v[14:17]
	v_mfma_f32_16x16x32_bf16 v[10:13], v[160:163], v[218:221], v[10:13]
	v_mfma_f32_16x16x32_bf16 v[54:57], v[164:167], v[180:183], v[54:57]
	v_mfma_f32_16x16x32_bf16 v[50:53], v[172:175], v[180:183], v[50:53]
	v_mfma_f32_16x16x32_bf16 v[38:41], v[164:167], v[188:191], v[38:41]
	v_mfma_f32_16x16x32_bf16 v[34:37], v[172:175], v[188:191], v[34:37]
	v_mfma_f32_16x16x32_bf16 v[22:25], v[164:167], v[206:209], v[22:25]
	v_mfma_f32_16x16x32_bf16 v[18:21], v[172:175], v[206:209], v[18:21]
	v_mfma_f32_16x16x32_bf16 v[6:9], v[164:167], v[214:217], v[6:9]
	v_mfma_f32_16x16x32_bf16 v[2:5], v[172:175], v[214:217], v[2:5]
	v_mfma_f32_16x16x32_bf16 v[54:57], v[168:171], v[184:187], v[54:57]
	v_mfma_f32_16x16x32_bf16 v[50:53], v[176:179], v[184:187], v[50:53]
	v_mfma_f32_16x16x32_bf16 v[38:41], v[168:171], v[192:195], v[38:41]
	v_mfma_f32_16x16x32_bf16 v[34:37], v[176:179], v[192:195], v[34:37]
	v_mfma_f32_16x16x32_bf16 v[22:25], v[168:171], v[210:213], v[22:25]
	v_mfma_f32_16x16x32_bf16 v[18:21], v[176:179], v[210:213], v[18:21]
	s_barrier
	v_mfma_f32_16x16x32_bf16 v[6:9], v[168:171], v[218:221], v[6:9]
	v_mfma_f32_16x16x32_bf16 v[2:5], v[176:179], v[218:221], v[2:5]
	s_add_i32 s44, s44, 2
	s_add_u32 s24, s24, 0x100
	s_addc_u32 s25, s25, 0
	s_add_u32 s42, s42, 0x100
	s_addc_u32 s43, s43, 0
	s_cmp_gt_u32 s44, 29
	s_cbranch_scc0 .LBB0_408
	s_and_b64 vcc, exec, s[12:13]
	s_cbranch_vccz .LBB0_411
	s_barrier

.LBB0_440:
	s_add_u32 s2, s18, 0xfff80080
	s_addc_u32 s10, s19, -1
	s_add_i32 s47, 0, 0x10000
	s_cmp_eq_u32 s46, 28
	s_cselect_b32 s29, s25, s10
	s_cselect_b32 s28, s34, s2
	s_cselect_b32 s11, s23, s45
	s_cselect_b32 s10, s43, s44
	s_add_u32 s100, s18, 0xfff80000
	s_addc_u32 s101, s19, -1
	s_add_i32 s2, 0, 0x14000
	v_add_u32_e32 v154, s47, v162
	v_add_u32_e32 v184, s2, v162
	s_mov_b32 m0, s38
	ds_read_b128 v[130:133], v154
	ds_read_b128 v[134:137], v154 offset:1024
	ds_read_b128 v[150:153], v154 offset:2048
	ds_read_b128 v[154:157], v154 offset:3072
	global_load_lds_dwordx4 v144, s[100:101]
	s_mov_b32 m0, s39
	ds_read_b128 v[158:161], v184
	ds_read_b128 v[176:179], v184 offset:1024
	ds_read_b128 v[180:183], v184 offset:2048
	ds_read_b128 v[184:187], v184 offset:3072
	global_load_lds_dwordx4 v148, s[100:101]
	s_add_i32 m0, s31, 0xc000
	ds_read_b128 v[188:191], v175
	ds_read_b128 v[192:195], v175 offset:1024
	ds_read_b128 v[206:209], v175 offset:2048
	ds_read_b128 v[210:213], v175 offset:3072
	global_load_lds_dwordx4 v144, s[18:19]
	s_add_i32 m0, s31, 0xe000
	ds_read_b128 v[214:217], v175 offset:4096
	ds_read_b128 v[218:221], v175 offset:5120
	ds_read_b128 v[222:225], v175 offset:6144
	ds_read_b128 v[226:229], v175 offset:7168
	global_load_lds_dwordx4 v148, s[18:19]
	s_waitcnt vmcnt(8)
	s_waitcnt lgkmcnt(0)
	s_barrier
	s_waitcnt lgkmcnt(0)
	v_mfma_f32_16x16x32_bf16 v[126:129], v[130:133], v[188:191], v[126:129]
	v_mfma_f32_16x16x32_bf16 v[122:125], v[150:153], v[188:191], v[122:125]
	v_mfma_f32_16x16x32_bf16 v[110:113], v[130:133], v[206:209], v[110:113]
	v_mfma_f32_16x16x32_bf16 v[106:109], v[150:153], v[206:209], v[106:109]
	v_mfma_f32_16x16x32_bf16 v[94:97], v[130:133], v[214:217], v[94:97]
	v_mfma_f32_16x16x32_bf16 v[90:93], v[150:153], v[214:217], v[90:93]
	v_mfma_f32_16x16x32_bf16 v[78:81], v[130:133], v[222:225], v[78:81]
	v_mfma_f32_16x16x32_bf16 v[74:77], v[150:153], v[222:225], v[74:77]
	v_mfma_f32_16x16x32_bf16 v[126:129], v[134:137], v[192:195], v[126:129]
	v_mfma_f32_16x16x32_bf16 v[122:125], v[154:157], v[192:195], v[122:125]
	v_mfma_f32_16x16x32_bf16 v[110:113], v[134:137], v[210:213], v[110:113]
	v_mfma_f32_16x16x32_bf16 v[106:109], v[154:157], v[210:213], v[106:109]
	v_mfma_f32_16x16x32_bf16 v[94:97], v[134:137], v[218:221], v[94:97]
	v_mfma_f32_16x16x32_bf16 v[90:93], v[154:157], v[218:221], v[90:93]
	v_mfma_f32_16x16x32_bf16 v[78:81], v[134:137], v[226:229], v[78:81]
	v_mfma_f32_16x16x32_bf16 v[74:77], v[154:157], v[226:229], v[74:77]
	v_mfma_f32_16x16x32_bf16 v[118:121], v[158:161], v[188:191], v[118:121]
	v_mfma_f32_16x16x32_bf16 v[114:117], v[180:183], v[188:191], v[114:117]
	v_mfma_f32_16x16x32_bf16 v[102:105], v[158:161], v[206:209], v[102:105]
	v_mfma_f32_16x16x32_bf16 v[98:101], v[180:183], v[206:209], v[98:101]
	v_mfma_f32_16x16x32_bf16 v[86:89], v[158:161], v[214:217], v[86:89]
	v_mfma_f32_16x16x32_bf16 v[82:85], v[180:183], v[214:217], v[82:85]
	v_mfma_f32_16x16x32_bf16 v[70:73], v[158:161], v[222:225], v[70:73]
	v_mfma_f32_16x16x32_bf16 v[66:69], v[180:183], v[222:225], v[66:69]
	v_mfma_f32_16x16x32_bf16 v[118:121], v[176:179], v[192:195], v[118:121]
	v_mfma_f32_16x16x32_bf16 v[114:117], v[184:187], v[192:195], v[114:117]
	v_mfma_f32_16x16x32_bf16 v[102:105], v[176:179], v[210:213], v[102:105]
	v_mfma_f32_16x16x32_bf16 v[98:101], v[184:187], v[210:213], v[98:101]
	v_mfma_f32_16x16x32_bf16 v[86:89], v[176:179], v[218:221], v[86:89]
	v_mfma_f32_16x16x32_bf16 v[82:85], v[184:187], v[218:221], v[82:85]
	s_barrier
	v_mfma_f32_16x16x32_bf16 v[70:73], v[176:179], v[226:229], v[70:73]
	v_mfma_f32_16x16x32_bf16 v[66:69], v[184:187], v[226:229], v[66:69]
	s_add_u32 s52, s10, 0x80000
	s_addc_u32 s53, s11, 0
	s_add_i32 s47, s47, s30
	s_mov_b32 m0, s47
	ds_read_b128 v[188:191], v175 offset:16384
	ds_read_b128 v[192:195], v175 offset:17408
	global_load_lds_dwordx4 v0, s[10:11]
	s_add_i32 m0, s47, 0x2000
	s_add_i32 s2, s2, s30
	ds_read_b128 v[206:209], v175 offset:18432
	ds_read_b128 v[210:213], v175 offset:19456
	global_load_lds_dwordx4 v138, s[10:11]
	s_mov_b32 m0, s2
	ds_read_b128 v[214:217], v175 offset:20480
	ds_read_b128 v[218:221], v175 offset:21504
	global_load_lds_dwordx4 v0, s[52:53]
	s_add_i32 m0, s2, 0x2000
	ds_read_b128 v[222:225], v175 offset:22528
	ds_read_b128 v[226:229], v175 offset:23552
	global_load_lds_dwordx4 v138, s[52:53]
	s_waitcnt vmcnt(6)
	s_waitcnt lgkmcnt(0)
	s_barrier
	s_waitcnt lgkmcnt(0)
	v_mfma_f32_16x16x32_bf16 v[62:65], v[130:133], v[188:191], v[62:65]
	v_mfma_f32_16x16x32_bf16 v[58:61], v[150:153], v[188:191], v[58:61]
	v_mfma_f32_16x16x32_bf16 v[46:49], v[130:133], v[206:209], v[46:49]
	v_mfma_f32_16x16x32_bf16 v[42:45], v[150:153], v[206:209], v[42:45]
	v_mfma_f32_16x16x32_bf16 v[30:33], v[130:133], v[214:217], v[30:33]
	v_mfma_f32_16x16x32_bf16 v[26:29], v[150:153], v[214:217], v[26:29]
	v_mfma_f32_16x16x32_bf16 v[14:17], v[130:133], v[222:225], v[14:17]
	v_mfma_f32_16x16x32_bf16 v[10:13], v[150:153], v[222:225], v[10:13]
	v_mfma_f32_16x16x32_bf16 v[62:65], v[134:137], v[192:195], v[62:65]
	v_mfma_f32_16x16x32_bf16 v[58:61], v[154:157], v[192:195], v[58:61]
	v_mfma_f32_16x16x32_bf16 v[46:49], v[134:137], v[210:213], v[46:49]
	v_mfma_f32_16x16x32_bf16 v[42:45], v[154:157], v[210:213], v[42:45]
	v_mfma_f32_16x16x32_bf16 v[30:33], v[134:137], v[218:221], v[30:33]
	v_mfma_f32_16x16x32_bf16 v[26:29], v[154:157], v[218:221], v[26:29]
	v_mfma_f32_16x16x32_bf16 v[14:17], v[134:137], v[226:229], v[14:17]
	v_mfma_f32_16x16x32_bf16 v[10:13], v[154:157], v[226:229], v[10:13]
	v_mfma_f32_16x16x32_bf16 v[54:57], v[158:161], v[188:191], v[54:57]
	v_mfma_f32_16x16x32_bf16 v[50:53], v[180:183], v[188:191], v[50:53]
	v_mfma_f32_16x16x32_bf16 v[38:41], v[158:161], v[206:209], v[38:41]
	v_mfma_f32_16x16x32_bf16 v[34:37], v[180:183], v[206:209], v[34:37]
	v_mfma_f32_16x16x32_bf16 v[22:25], v[158:161], v[214:217], v[22:25]
	v_mfma_f32_16x16x32_bf16 v[18:21], v[180:183], v[214:217], v[18:21]
	v_mfma_f32_16x16x32_bf16 v[6:9], v[158:161], v[222:225], v[6:9]
	v_mfma_f32_16x16x32_bf16 v[2:5], v[180:183], v[222:225], v[2:5]
	v_mfma_f32_16x16x32_bf16 v[54:57], v[176:179], v[192:195], v[54:57]
	v_mfma_f32_16x16x32_bf16 v[50:53], v[184:187], v[192:195], v[50:53]
	v_mfma_f32_16x16x32_bf16 v[38:41], v[176:179], v[210:213], v[38:41]
	v_mfma_f32_16x16x32_bf16 v[34:37], v[184:187], v[210:213], v[34:37]
	v_mfma_f32_16x16x32_bf16 v[22:25], v[176:179], v[218:221], v[22:25]
	v_mfma_f32_16x16x32_bf16 v[18:21], v[184:187], v[218:221], v[18:21]
	s_barrier
	v_mfma_f32_16x16x32_bf16 v[6:9], v[176:179], v[226:229], v[6:9]
	v_mfma_f32_16x16x32_bf16 v[2:5], v[184:187], v[226:229], v[2:5]
	s_add_u32 s28, s28, 0x80000
	s_addc_u32 s29, s29, 0
	s_add_u32 s100, s28, 0xfff80000
	s_addc_u32 s101, s29, -1
	s_add_i32 s2, 0, 0x18000
	s_add_i32 s47, 0, 0x1c000
	v_add_u32_e32 v154, s2, v162
	v_add_u32_e32 v184, s47, v162
	s_mov_b32 m0, s31
	ds_read_b128 v[130:133], v154
	ds_read_b128 v[134:137], v154 offset:1024
	ds_read_b128 v[150:153], v154 offset:2048
	ds_read_b128 v[154:157], v154 offset:3072
	global_load_lds_dwordx4 v142, s[100:101]
	s_mov_b32 m0, s35
	ds_read_b128 v[158:161], v184
	ds_read_b128 v[176:179], v184 offset:1024
	ds_read_b128 v[180:183], v184 offset:2048
	ds_read_b128 v[184:187], v184 offset:3072
	global_load_lds_dwordx4 v140, s[100:101]
	s_mov_b32 m0, s36
	ds_read_b128 v[188:191], v175 offset:32768
	ds_read_b128 v[192:195], v175 offset:33792
	ds_read_b128 v[206:209], v175 offset:34816
	ds_read_b128 v[210:213], v175 offset:35840
	global_load_lds_dwordx4 v142, s[28:29]
	s_mov_b32 m0, s37
	ds_read_b128 v[214:217], v175 offset:36864
	ds_read_b128 v[218:221], v175 offset:37888
	ds_read_b128 v[222:225], v175 offset:38912
	ds_read_b128 v[226:229], v175 offset:39936
	global_load_lds_dwordx4 v140, s[28:29]
	s_waitcnt vmcnt(8)
	s_waitcnt lgkmcnt(0)
	s_barrier
	s_waitcnt lgkmcnt(0)
	v_mfma_f32_16x16x32_bf16 v[126:129], v[130:133], v[188:191], v[126:129]
	v_mfma_f32_16x16x32_bf16 v[122:125], v[150:153], v[188:191], v[122:125]
	v_mfma_f32_16x16x32_bf16 v[110:113], v[130:133], v[206:209], v[110:113]
	v_mfma_f32_16x16x32_bf16 v[106:109], v[150:153], v[206:209], v[106:109]
	v_mfma_f32_16x16x32_bf16 v[94:97], v[130:133], v[214:217], v[94:97]
	v_mfma_f32_16x16x32_bf16 v[90:93], v[150:153], v[214:217], v[90:93]
	v_mfma_f32_16x16x32_bf16 v[78:81], v[130:133], v[222:225], v[78:81]
	v_mfma_f32_16x16x32_bf16 v[74:77], v[150:153], v[222:225], v[74:77]
	v_mfma_f32_16x16x32_bf16 v[126:129], v[134:137], v[192:195], v[126:129]
	v_mfma_f32_16x16x32_bf16 v[122:125], v[154:157], v[192:195], v[122:125]
	v_mfma_f32_16x16x32_bf16 v[110:113], v[134:137], v[210:213], v[110:113]
	v_mfma_f32_16x16x32_bf16 v[106:109], v[154:157], v[210:213], v[106:109]
	v_mfma_f32_16x16x32_bf16 v[94:97], v[134:137], v[218:221], v[94:97]
	v_mfma_f32_16x16x32_bf16 v[90:93], v[154:157], v[218:221], v[90:93]
	v_mfma_f32_16x16x32_bf16 v[78:81], v[134:137], v[226:229], v[78:81]
	v_mfma_f32_16x16x32_bf16 v[74:77], v[154:157], v[226:229], v[74:77]
	v_mfma_f32_16x16x32_bf16 v[118:121], v[158:161], v[188:191], v[118:121]
	v_mfma_f32_16x16x32_bf16 v[114:117], v[180:183], v[188:191], v[114:117]
	v_mfma_f32_16x16x32_bf16 v[102:105], v[158:161], v[206:209], v[102:105]
	v_mfma_f32_16x16x32_bf16 v[98:101], v[180:183], v[206:209], v[98:101]
	v_mfma_f32_16x16x32_bf16 v[86:89], v[158:161], v[214:217], v[86:89]
	v_mfma_f32_16x16x32_bf16 v[82:85], v[180:183], v[214:217], v[82:85]
	v_mfma_f32_16x16x32_bf16 v[70:73], v[158:161], v[222:225], v[70:73]
	v_mfma_f32_16x16x32_bf16 v[66:69], v[180:183], v[222:225], v[66:69]
	v_mfma_f32_16x16x32_bf16 v[118:121], v[176:179], v[192:195], v[118:121]
	v_mfma_f32_16x16x32_bf16 v[114:117], v[184:187], v[192:195], v[114:117]
	v_mfma_f32_16x16x32_bf16 v[102:105], v[176:179], v[210:213], v[102:105]
	v_mfma_f32_16x16x32_bf16 v[98:101], v[184:187], v[210:213], v[98:101]
	v_mfma_f32_16x16x32_bf16 v[86:89], v[176:179], v[218:221], v[86:89]
	v_mfma_f32_16x16x32_bf16 v[82:85], v[184:187], v[218:221], v[82:85]
	s_barrier
	v_mfma_f32_16x16x32_bf16 v[70:73], v[176:179], v[226:229], v[70:73]
	v_mfma_f32_16x16x32_bf16 v[66:69], v[184:187], v[226:229], v[66:69]
	s_add_u32 s10, s10, 0x80080
	s_addc_u32 s11, s11, 0
	s_add_u32 s52, s52, 0xfff80080
	s_addc_u32 s53, s53, -1
	s_add_i32 s2, s2, s30
	s_mov_b32 m0, s2
	ds_read_b128 v[188:191], v175 offset:49152
	ds_read_b128 v[192:195], v175 offset:50176
	global_load_lds_dwordx4 v0, s[52:53]
	s_add_i32 m0, s2, 0x2000
	s_add_i32 s2, s47, s30
	ds_read_b128 v[206:209], v175 offset:51200
	ds_read_b128 v[210:213], v175 offset:52224
	global_load_lds_dwordx4 v138, s[52:53]
	s_mov_b32 m0, s2
	ds_read_b128 v[214:217], v175 offset:53248
	ds_read_b128 v[218:221], v175 offset:54272
	global_load_lds_dwordx4 v0, s[10:11]
	s_add_i32 m0, s2, 0x2000
	ds_read_b128 v[222:225], v175 offset:55296
	ds_read_b128 v[226:229], v175 offset:56320
	global_load_lds_dwordx4 v138, s[10:11]
	s_waitcnt vmcnt(6)
	s_waitcnt lgkmcnt(0)
	s_barrier
	s_waitcnt lgkmcnt(0)
	v_mfma_f32_16x16x32_bf16 v[62:65], v[130:133], v[188:191], v[62:65]
	v_mfma_f32_16x16x32_bf16 v[58:61], v[150:153], v[188:191], v[58:61]
	v_mfma_f32_16x16x32_bf16 v[46:49], v[130:133], v[206:209], v[46:49]
	v_mfma_f32_16x16x32_bf16 v[42:45], v[150:153], v[206:209], v[42:45]
	v_mfma_f32_16x16x32_bf16 v[30:33], v[130:133], v[214:217], v[30:33]
	v_mfma_f32_16x16x32_bf16 v[26:29], v[150:153], v[214:217], v[26:29]
	v_mfma_f32_16x16x32_bf16 v[14:17], v[130:133], v[222:225], v[14:17]
	v_mfma_f32_16x16x32_bf16 v[10:13], v[150:153], v[222:225], v[10:13]
	v_mfma_f32_16x16x32_bf16 v[62:65], v[134:137], v[192:195], v[62:65]
	v_mfma_f32_16x16x32_bf16 v[58:61], v[154:157], v[192:195], v[58:61]
	v_mfma_f32_16x16x32_bf16 v[46:49], v[134:137], v[210:213], v[46:49]
	v_mfma_f32_16x16x32_bf16 v[42:45], v[154:157], v[210:213], v[42:45]
	v_mfma_f32_16x16x32_bf16 v[30:33], v[134:137], v[218:221], v[30:33]
	v_mfma_f32_16x16x32_bf16 v[26:29], v[154:157], v[218:221], v[26:29]
	v_mfma_f32_16x16x32_bf16 v[14:17], v[134:137], v[226:229], v[14:17]
	v_mfma_f32_16x16x32_bf16 v[10:13], v[154:157], v[226:229], v[10:13]
	v_mfma_f32_16x16x32_bf16 v[54:57], v[158:161], v[188:191], v[54:57]
	v_mfma_f32_16x16x32_bf16 v[50:53], v[180:183], v[188:191], v[50:53]
	v_mfma_f32_16x16x32_bf16 v[38:41], v[158:161], v[206:209], v[38:41]
	v_mfma_f32_16x16x32_bf16 v[34:37], v[180:183], v[206:209], v[34:37]
	v_mfma_f32_16x16x32_bf16 v[22:25], v[158:161], v[214:217], v[22:25]
	v_mfma_f32_16x16x32_bf16 v[18:21], v[180:183], v[214:217], v[18:21]
	v_mfma_f32_16x16x32_bf16 v[6:9], v[158:161], v[222:225], v[6:9]
	v_mfma_f32_16x16x32_bf16 v[2:5], v[180:183], v[222:225], v[2:5]
	v_mfma_f32_16x16x32_bf16 v[54:57], v[176:179], v[192:195], v[54:57]
	v_mfma_f32_16x16x32_bf16 v[50:53], v[184:187], v[192:195], v[50:53]
	v_mfma_f32_16x16x32_bf16 v[38:41], v[176:179], v[210:213], v[38:41]
	v_mfma_f32_16x16x32_bf16 v[34:37], v[184:187], v[210:213], v[34:37]
	v_mfma_f32_16x16x32_bf16 v[22:25], v[176:179], v[218:221], v[22:25]
	v_mfma_f32_16x16x32_bf16 v[18:21], v[184:187], v[218:221], v[18:21]
	s_barrier
	v_mfma_f32_16x16x32_bf16 v[6:9], v[176:179], v[226:229], v[6:9]
	v_mfma_f32_16x16x32_bf16 v[2:5], v[184:187], v[226:229], v[2:5]
	s_add_i32 s46, s46, 2
	s_add_u32 s18, s18, 0x100
	s_addc_u32 s19, s19, 0
	s_add_u32 s44, s44, 0x100
	s_addc_u32 s45, s45, 0
	s_cmp_gt_u32 s46, 29
	s_cbranch_scc0 .LBB0_440
	s_and_b64 vcc, exec, s[20:21]
	s_cbranch_vccz .LBB0_443
	s_barrier

.LBB0_1102:
	s_add_u32 s2, s22, 0xfff80080
	s_addc_u32 s20, s23, -1
	s_add_i32 s45, 0, 0x10000
	s_cmp_eq_u32 s44, 28
	s_cselect_b32 s25, s15, s20
	s_cselect_b32 s24, s40, s2
	s_cselect_b32 s21, s13, s43
	s_cselect_b32 s20, s41, s42
	s_add_u32 s100, s22, 0xfff80000
	s_addc_u32 s101, s23, -1
	s_add_i32 s2, 0, 0x14000
	v_add_u32_e32 v142, s45, v226
	v_add_u32_e32 v160, s2, v226
	s_mov_b32 m0, s38
	ds_read_b128 v[130:133], v142
	ds_read_b128 v[134:137], v142 offset:1024
	ds_read_b128 v[138:141], v142 offset:2048
	ds_read_b128 v[142:145], v142 offset:3072
	global_load_lds_dwordx4 v194, s[100:101]
	s_mov_b32 m0, s39
	ds_read_b128 v[148:151], v160
	ds_read_b128 v[152:155], v160 offset:1024
	ds_read_b128 v[156:159], v160 offset:2048
	ds_read_b128 v[160:163], v160 offset:3072
	global_load_lds_dwordx4 v206, s[100:101]
	s_add_i32 m0, s30, 0xc000
	ds_read_b128 v[164:167], v228
	ds_read_b128 v[168:171], v228 offset:1024
	ds_read_b128 v[172:175], v228 offset:2048
	ds_read_b128 v[176:179], v228 offset:3072
	global_load_lds_dwordx4 v194, s[22:23]
	s_add_i32 m0, s30, 0xe000
	ds_read_b128 v[180:183], v228 offset:4096
	ds_read_b128 v[184:187], v228 offset:5120
	ds_read_b128 v[208:211], v228 offset:6144
	ds_read_b128 v[212:215], v228 offset:7168
	global_load_lds_dwordx4 v206, s[22:23]
	s_waitcnt vmcnt(8)
	s_waitcnt lgkmcnt(0)
	s_barrier
	s_waitcnt lgkmcnt(0)
	v_mfma_f32_16x16x32_bf16 v[126:129], v[130:133], v[164:167], v[126:129]
	v_mfma_f32_16x16x32_bf16 v[122:125], v[138:141], v[164:167], v[122:125]
	v_mfma_f32_16x16x32_bf16 v[110:113], v[130:133], v[172:175], v[110:113]
	v_mfma_f32_16x16x32_bf16 v[106:109], v[138:141], v[172:175], v[106:109]
	v_mfma_f32_16x16x32_bf16 v[94:97], v[130:133], v[180:183], v[94:97]
	v_mfma_f32_16x16x32_bf16 v[90:93], v[138:141], v[180:183], v[90:93]
	v_mfma_f32_16x16x32_bf16 v[78:81], v[130:133], v[208:211], v[78:81]
	v_mfma_f32_16x16x32_bf16 v[74:77], v[138:141], v[208:211], v[74:77]
	v_mfma_f32_16x16x32_bf16 v[126:129], v[134:137], v[168:171], v[126:129]
	v_mfma_f32_16x16x32_bf16 v[122:125], v[142:145], v[168:171], v[122:125]
	v_mfma_f32_16x16x32_bf16 v[110:113], v[134:137], v[176:179], v[110:113]
	v_mfma_f32_16x16x32_bf16 v[106:109], v[142:145], v[176:179], v[106:109]
	v_mfma_f32_16x16x32_bf16 v[94:97], v[134:137], v[184:187], v[94:97]
	v_mfma_f32_16x16x32_bf16 v[90:93], v[142:145], v[184:187], v[90:93]
	v_mfma_f32_16x16x32_bf16 v[78:81], v[134:137], v[212:215], v[78:81]
	v_mfma_f32_16x16x32_bf16 v[74:77], v[142:145], v[212:215], v[74:77]
	v_mfma_f32_16x16x32_bf16 v[118:121], v[148:151], v[164:167], v[118:121]
	v_mfma_f32_16x16x32_bf16 v[114:117], v[156:159], v[164:167], v[114:117]
	v_mfma_f32_16x16x32_bf16 v[102:105], v[148:151], v[172:175], v[102:105]
	v_mfma_f32_16x16x32_bf16 v[98:101], v[156:159], v[172:175], v[98:101]
	v_mfma_f32_16x16x32_bf16 v[86:89], v[148:151], v[180:183], v[86:89]
	v_mfma_f32_16x16x32_bf16 v[82:85], v[156:159], v[180:183], v[82:85]
	v_mfma_f32_16x16x32_bf16 v[70:73], v[148:151], v[208:211], v[70:73]
	v_mfma_f32_16x16x32_bf16 v[66:69], v[156:159], v[208:211], v[66:69]
	v_mfma_f32_16x16x32_bf16 v[118:121], v[152:155], v[168:171], v[118:121]
	v_mfma_f32_16x16x32_bf16 v[114:117], v[160:163], v[168:171], v[114:117]
	v_mfma_f32_16x16x32_bf16 v[102:105], v[152:155], v[176:179], v[102:105]
	v_mfma_f32_16x16x32_bf16 v[98:101], v[160:163], v[176:179], v[98:101]
	v_mfma_f32_16x16x32_bf16 v[86:89], v[152:155], v[184:187], v[86:89]
	v_mfma_f32_16x16x32_bf16 v[82:85], v[160:163], v[184:187], v[82:85]
	s_barrier
	v_mfma_f32_16x16x32_bf16 v[70:73], v[152:155], v[212:215], v[70:73]
	v_mfma_f32_16x16x32_bf16 v[66:69], v[160:163], v[212:215], v[66:69]
	s_add_u32 s46, s20, 0x80000
	s_addc_u32 s47, s21, 0
	s_add_i32 s45, s45, s29
	s_mov_b32 m0, s45
	ds_read_b128 v[164:167], v228 offset:16384
	ds_read_b128 v[168:171], v228 offset:17408
	global_load_lds_dwordx4 v0, s[20:21]
	s_add_i32 m0, s45, 0x2000
	s_add_i32 s2, s2, s29
	ds_read_b128 v[172:175], v228 offset:18432
	ds_read_b128 v[176:179], v228 offset:19456
	global_load_lds_dwordx4 v188, s[20:21]
	s_mov_b32 m0, s2
	ds_read_b128 v[180:183], v228 offset:20480
	ds_read_b128 v[184:187], v228 offset:21504
	global_load_lds_dwordx4 v0, s[46:47]
	s_add_i32 m0, s2, 0x2000
	ds_read_b128 v[208:211], v228 offset:22528
	ds_read_b128 v[212:215], v228 offset:23552
	global_load_lds_dwordx4 v188, s[46:47]
	s_waitcnt vmcnt(6)
	s_waitcnt lgkmcnt(0)
	s_barrier
	s_waitcnt lgkmcnt(0)
	v_mfma_f32_16x16x32_bf16 v[62:65], v[130:133], v[164:167], v[62:65]
	v_mfma_f32_16x16x32_bf16 v[58:61], v[138:141], v[164:167], v[58:61]
	v_mfma_f32_16x16x32_bf16 v[46:49], v[130:133], v[172:175], v[46:49]
	v_mfma_f32_16x16x32_bf16 v[42:45], v[138:141], v[172:175], v[42:45]
	v_mfma_f32_16x16x32_bf16 v[30:33], v[130:133], v[180:183], v[30:33]
	v_mfma_f32_16x16x32_bf16 v[26:29], v[138:141], v[180:183], v[26:29]
	v_mfma_f32_16x16x32_bf16 v[14:17], v[130:133], v[208:211], v[14:17]
	v_mfma_f32_16x16x32_bf16 v[10:13], v[138:141], v[208:211], v[10:13]
	v_mfma_f32_16x16x32_bf16 v[62:65], v[134:137], v[168:171], v[62:65]
	v_mfma_f32_16x16x32_bf16 v[58:61], v[142:145], v[168:171], v[58:61]
	v_mfma_f32_16x16x32_bf16 v[46:49], v[134:137], v[176:179], v[46:49]
	v_mfma_f32_16x16x32_bf16 v[42:45], v[142:145], v[176:179], v[42:45]
	v_mfma_f32_16x16x32_bf16 v[30:33], v[134:137], v[184:187], v[30:33]
	v_mfma_f32_16x16x32_bf16 v[26:29], v[142:145], v[184:187], v[26:29]
	v_mfma_f32_16x16x32_bf16 v[14:17], v[134:137], v[212:215], v[14:17]
	v_mfma_f32_16x16x32_bf16 v[10:13], v[142:145], v[212:215], v[10:13]
	v_mfma_f32_16x16x32_bf16 v[54:57], v[148:151], v[164:167], v[54:57]
	v_mfma_f32_16x16x32_bf16 v[50:53], v[156:159], v[164:167], v[50:53]
	v_mfma_f32_16x16x32_bf16 v[38:41], v[148:151], v[172:175], v[38:41]
	v_mfma_f32_16x16x32_bf16 v[34:37], v[156:159], v[172:175], v[34:37]
	v_mfma_f32_16x16x32_bf16 v[22:25], v[148:151], v[180:183], v[22:25]
	v_mfma_f32_16x16x32_bf16 v[18:21], v[156:159], v[180:183], v[18:21]
	v_mfma_f32_16x16x32_bf16 v[6:9], v[148:151], v[208:211], v[6:9]
	v_mfma_f32_16x16x32_bf16 v[2:5], v[156:159], v[208:211], v[2:5]
	v_mfma_f32_16x16x32_bf16 v[54:57], v[152:155], v[168:171], v[54:57]
	v_mfma_f32_16x16x32_bf16 v[50:53], v[160:163], v[168:171], v[50:53]
	v_mfma_f32_16x16x32_bf16 v[38:41], v[152:155], v[176:179], v[38:41]
	v_mfma_f32_16x16x32_bf16 v[34:37], v[160:163], v[176:179], v[34:37]
	v_mfma_f32_16x16x32_bf16 v[22:25], v[152:155], v[184:187], v[22:25]
	v_mfma_f32_16x16x32_bf16 v[18:21], v[160:163], v[184:187], v[18:21]
	s_barrier
	v_mfma_f32_16x16x32_bf16 v[6:9], v[152:155], v[212:215], v[6:9]
	v_mfma_f32_16x16x32_bf16 v[2:5], v[160:163], v[212:215], v[2:5]
	s_add_u32 s24, s24, 0x80000
	s_addc_u32 s25, s25, 0
	s_add_u32 s100, s24, 0xfff80000
	s_addc_u32 s101, s25, -1
	s_add_i32 s2, 0, 0x18000
	s_add_i32 s45, 0, 0x1c000
	v_add_u32_e32 v142, s2, v226
	v_add_u32_e32 v160, s45, v226
	s_mov_b32 m0, s30
	ds_read_b128 v[130:133], v142
	ds_read_b128 v[134:137], v142 offset:1024
	ds_read_b128 v[138:141], v142 offset:2048
	ds_read_b128 v[142:145], v142 offset:3072
	global_load_lds_dwordx4 v192, s[100:101]
	s_mov_b32 m0, s31
	ds_read_b128 v[148:151], v160
	ds_read_b128 v[152:155], v160 offset:1024
	ds_read_b128 v[156:159], v160 offset:2048
	ds_read_b128 v[160:163], v160 offset:3072
	global_load_lds_dwordx4 v190, s[100:101]
	s_mov_b32 m0, s35
	ds_read_b128 v[164:167], v228 offset:32768
	ds_read_b128 v[168:171], v228 offset:33792
	ds_read_b128 v[172:175], v228 offset:34816
	ds_read_b128 v[176:179], v228 offset:35840
	global_load_lds_dwordx4 v192, s[24:25]
	s_mov_b32 m0, s36
	ds_read_b128 v[180:183], v228 offset:36864
	ds_read_b128 v[184:187], v228 offset:37888
	ds_read_b128 v[208:211], v228 offset:38912
	ds_read_b128 v[212:215], v228 offset:39936
	global_load_lds_dwordx4 v190, s[24:25]
	s_waitcnt vmcnt(8)
	s_waitcnt lgkmcnt(0)
	s_barrier
	s_waitcnt lgkmcnt(0)
	v_mfma_f32_16x16x32_bf16 v[126:129], v[130:133], v[164:167], v[126:129]
	v_mfma_f32_16x16x32_bf16 v[122:125], v[138:141], v[164:167], v[122:125]
	v_mfma_f32_16x16x32_bf16 v[110:113], v[130:133], v[172:175], v[110:113]
	v_mfma_f32_16x16x32_bf16 v[106:109], v[138:141], v[172:175], v[106:109]
	v_mfma_f32_16x16x32_bf16 v[94:97], v[130:133], v[180:183], v[94:97]
	v_mfma_f32_16x16x32_bf16 v[90:93], v[138:141], v[180:183], v[90:93]
	v_mfma_f32_16x16x32_bf16 v[78:81], v[130:133], v[208:211], v[78:81]
	v_mfma_f32_16x16x32_bf16 v[74:77], v[138:141], v[208:211], v[74:77]
	v_mfma_f32_16x16x32_bf16 v[126:129], v[134:137], v[168:171], v[126:129]
	v_mfma_f32_16x16x32_bf16 v[122:125], v[142:145], v[168:171], v[122:125]
	v_mfma_f32_16x16x32_bf16 v[110:113], v[134:137], v[176:179], v[110:113]
	v_mfma_f32_16x16x32_bf16 v[106:109], v[142:145], v[176:179], v[106:109]
	v_mfma_f32_16x16x32_bf16 v[94:97], v[134:137], v[184:187], v[94:97]
	v_mfma_f32_16x16x32_bf16 v[90:93], v[142:145], v[184:187], v[90:93]
	v_mfma_f32_16x16x32_bf16 v[78:81], v[134:137], v[212:215], v[78:81]
	v_mfma_f32_16x16x32_bf16 v[74:77], v[142:145], v[212:215], v[74:77]
	v_mfma_f32_16x16x32_bf16 v[118:121], v[148:151], v[164:167], v[118:121]
	v_mfma_f32_16x16x32_bf16 v[114:117], v[156:159], v[164:167], v[114:117]
	v_mfma_f32_16x16x32_bf16 v[102:105], v[148:151], v[172:175], v[102:105]
	v_mfma_f32_16x16x32_bf16 v[98:101], v[156:159], v[172:175], v[98:101]
	v_mfma_f32_16x16x32_bf16 v[86:89], v[148:151], v[180:183], v[86:89]
	v_mfma_f32_16x16x32_bf16 v[82:85], v[156:159], v[180:183], v[82:85]
	v_mfma_f32_16x16x32_bf16 v[70:73], v[148:151], v[208:211], v[70:73]
	v_mfma_f32_16x16x32_bf16 v[66:69], v[156:159], v[208:211], v[66:69]
	v_mfma_f32_16x16x32_bf16 v[118:121], v[152:155], v[168:171], v[118:121]
	v_mfma_f32_16x16x32_bf16 v[114:117], v[160:163], v[168:171], v[114:117]
	v_mfma_f32_16x16x32_bf16 v[102:105], v[152:155], v[176:179], v[102:105]
	v_mfma_f32_16x16x32_bf16 v[98:101], v[160:163], v[176:179], v[98:101]
	v_mfma_f32_16x16x32_bf16 v[86:89], v[152:155], v[184:187], v[86:89]
	v_mfma_f32_16x16x32_bf16 v[82:85], v[160:163], v[184:187], v[82:85]
	s_barrier
	v_mfma_f32_16x16x32_bf16 v[70:73], v[152:155], v[212:215], v[70:73]
	v_mfma_f32_16x16x32_bf16 v[66:69], v[160:163], v[212:215], v[66:69]
	s_add_u32 s20, s20, 0x80080
	s_addc_u32 s21, s21, 0
	s_add_u32 s46, s46, 0xfff80080
	s_addc_u32 s47, s47, -1
	s_add_i32 s2, s2, s29
	s_mov_b32 m0, s2
	ds_read_b128 v[164:167], v228 offset:49152
	ds_read_b128 v[168:171], v228 offset:50176
	global_load_lds_dwordx4 v0, s[46:47]
	s_add_i32 m0, s2, 0x2000
	s_add_i32 s2, s45, s29
	ds_read_b128 v[172:175], v228 offset:51200
	ds_read_b128 v[176:179], v228 offset:52224
	global_load_lds_dwordx4 v188, s[46:47]
	s_mov_b32 m0, s2
	ds_read_b128 v[180:183], v228 offset:53248
	ds_read_b128 v[184:187], v228 offset:54272
	global_load_lds_dwordx4 v0, s[20:21]
	s_add_i32 m0, s2, 0x2000
	ds_read_b128 v[208:211], v228 offset:55296
	ds_read_b128 v[212:215], v228 offset:56320
	global_load_lds_dwordx4 v188, s[20:21]
	s_waitcnt vmcnt(6)
	s_waitcnt lgkmcnt(0)
	s_barrier
	s_waitcnt lgkmcnt(0)
	v_mfma_f32_16x16x32_bf16 v[62:65], v[130:133], v[164:167], v[62:65]
	v_mfma_f32_16x16x32_bf16 v[58:61], v[138:141], v[164:167], v[58:61]
	v_mfma_f32_16x16x32_bf16 v[46:49], v[130:133], v[172:175], v[46:49]
	v_mfma_f32_16x16x32_bf16 v[42:45], v[138:141], v[172:175], v[42:45]
	v_mfma_f32_16x16x32_bf16 v[30:33], v[130:133], v[180:183], v[30:33]
	v_mfma_f32_16x16x32_bf16 v[26:29], v[138:141], v[180:183], v[26:29]
	v_mfma_f32_16x16x32_bf16 v[14:17], v[130:133], v[208:211], v[14:17]
	v_mfma_f32_16x16x32_bf16 v[10:13], v[138:141], v[208:211], v[10:13]
	v_mfma_f32_16x16x32_bf16 v[62:65], v[134:137], v[168:171], v[62:65]
	v_mfma_f32_16x16x32_bf16 v[58:61], v[142:145], v[168:171], v[58:61]
	v_mfma_f32_16x16x32_bf16 v[46:49], v[134:137], v[176:179], v[46:49]
	v_mfma_f32_16x16x32_bf16 v[42:45], v[142:145], v[176:179], v[42:45]
	v_mfma_f32_16x16x32_bf16 v[30:33], v[134:137], v[184:187], v[30:33]
	v_mfma_f32_16x16x32_bf16 v[26:29], v[142:145], v[184:187], v[26:29]
	v_mfma_f32_16x16x32_bf16 v[14:17], v[134:137], v[212:215], v[14:17]
	v_mfma_f32_16x16x32_bf16 v[10:13], v[142:145], v[212:215], v[10:13]
	v_mfma_f32_16x16x32_bf16 v[54:57], v[148:151], v[164:167], v[54:57]
	v_mfma_f32_16x16x32_bf16 v[50:53], v[156:159], v[164:167], v[50:53]
	v_mfma_f32_16x16x32_bf16 v[38:41], v[148:151], v[172:175], v[38:41]
	v_mfma_f32_16x16x32_bf16 v[34:37], v[156:159], v[172:175], v[34:37]
	v_mfma_f32_16x16x32_bf16 v[22:25], v[148:151], v[180:183], v[22:25]
	v_mfma_f32_16x16x32_bf16 v[18:21], v[156:159], v[180:183], v[18:21]
	v_mfma_f32_16x16x32_bf16 v[6:9], v[148:151], v[208:211], v[6:9]
	v_mfma_f32_16x16x32_bf16 v[2:5], v[156:159], v[208:211], v[2:5]
	v_mfma_f32_16x16x32_bf16 v[54:57], v[152:155], v[168:171], v[54:57]
	v_mfma_f32_16x16x32_bf16 v[50:53], v[160:163], v[168:171], v[50:53]
	v_mfma_f32_16x16x32_bf16 v[38:41], v[152:155], v[176:179], v[38:41]
	v_mfma_f32_16x16x32_bf16 v[34:37], v[160:163], v[176:179], v[34:37]
	v_mfma_f32_16x16x32_bf16 v[22:25], v[152:155], v[184:187], v[22:25]
	v_mfma_f32_16x16x32_bf16 v[18:21], v[160:163], v[184:187], v[18:21]
	s_barrier
	v_mfma_f32_16x16x32_bf16 v[6:9], v[152:155], v[212:215], v[6:9]
	v_mfma_f32_16x16x32_bf16 v[2:5], v[160:163], v[212:215], v[2:5]
	s_add_i32 s44, s44, 2
	s_add_u32 s22, s22, 0x100
	s_addc_u32 s23, s23, 0
	s_add_u32 s42, s42, 0x100
	s_addc_u32 s43, s43, 0
	s_cmp_gt_u32 s44, 29
	s_cbranch_scc0 .LBB0_1102
	v_lshl_or_b32 v210, s3, 8, v227
	v_lshl_add_u32 v224, s34, 8, v147
	v_ashrrev_i32_e32 v211, 31, v210
	v_lshlrev_b64 v[130:131], 1, v[210:211]
	v_ashrrev_i32_e32 v225, 31, v224
	v_lshl_add_u64 v[132:133], s[8:9], 0, v[130:131]
	v_lshlrev_b64 v[134:135], 12, v[224:225]
	v_lshl_add_u64 v[136:137], v[132:133], 0, v[134:135]
	global_load_dwordx4 v[240:243], v[136:137], off
	global_load_dwordx4 v[244:247], v[136:137], off offset:256
	v_or_b32_e32 v222, 16, v224
	v_or_b32_e32 v220, 32, v224
	v_or_b32_e32 v218, 48, v224
	v_add_u32_e32 v216, 0x80, v224
	v_add_u32_e32 v214, 0x90, v224
	v_add_u32_e32 v212, 0xa0, v224
	v_add_u32_e32 v208, 0xb0, v224
	v_ashrrev_i32_e32 v223, 31, v222
	v_ashrrev_i32_e32 v221, 31, v220
	v_ashrrev_i32_e32 v219, 31, v218
	v_ashrrev_i32_e32 v217, 31, v216
	v_ashrrev_i32_e32 v215, 31, v214
	v_ashrrev_i32_e32 v213, 31, v212
	v_ashrrev_i32_e32 v209, 31, v208
	v_lshlrev_b64 v[136:137], 12, v[222:223]
	v_lshlrev_b64 v[138:139], 12, v[220:221]
	v_lshlrev_b64 v[140:141], 12, v[218:219]
	v_lshlrev_b64 v[142:143], 12, v[216:217]
	v_lshlrev_b64 v[144:145], 12, v[214:215]
	v_lshlrev_b64 v[148:149], 12, v[212:213]
	v_lshlrev_b64 v[150:151], 12, v[208:209]
	v_lshl_add_u64 v[134:135], s[8:9], 0, v[134:135]
	v_lshl_add_u64 v[136:137], v[132:133], 0, v[136:137]
	v_lshl_add_u64 v[138:139], v[132:133], 0, v[138:139]
	v_lshl_add_u64 v[140:141], v[132:133], 0, v[140:141]
	v_lshl_add_u64 v[142:143], v[132:133], 0, v[142:143]
	v_lshl_add_u64 v[144:145], v[132:133], 0, v[144:145]
	v_lshl_add_u64 v[236:237], v[132:133], 0, v[148:149]
	v_lshl_add_u64 v[132:133], v[132:133], 0, v[150:151]
	v_lshl_add_u64 v[248:249], v[134:135], 0, v[130:131]
	global_load_dwordx4 v[184:187], v[136:137], off
	global_load_dwordx4 v[180:183], v[136:137], off offset:256
	global_load_dwordx4 v[176:179], v[138:139], off
	global_load_dwordx4 v[172:175], v[138:139], off offset:256
	global_load_dwordx4 v[168:171], v[140:141], off
	global_load_dwordx4 v[164:167], v[140:141], off offset:256
	global_load_dwordx4 v[160:163], v[142:143], off
	global_load_dwordx4 v[156:159], v[142:143], off offset:256
	global_load_dwordx4 v[152:155], v[144:145], off
	global_load_dwordx4 v[148:151], v[144:145], off offset:256
	s_nop 0
	global_load_dwordx4 v[142:145], v[236:237], off
	global_load_dwordx4 v[138:141], v[236:237], off offset:256
	global_load_dwordx4 v[134:137], v[132:133], off
	s_nop 0
	global_load_dwordx4 v[130:133], v[132:133], off offset:256
	s_lshl_b32 s20, s3, 2
	s_ashr_i32 s21, s20, 31
	s_waitcnt vmcnt(0)
	v_lshlrev_b32_e32 v236, 16, v240
	v_and_b32_e32 v237, 0xffff0000, v240
	v_lshlrev_b32_e32 v250, 16, v242
	v_and_b32_e32 v251, 0xffff0000, v242
	v_lshlrev_b32_e32 v242, 16, v243
	v_and_b32_e32 v243, 0xffff0000, v243
	v_lshlrev_b32_e32 v240, 16, v241
	v_and_b32_e32 v241, 0xffff0000, v241
	v_pk_add_f32 v[126:127], v[126:127], v[236:237]
	v_pk_add_f32 v[236:237], v[124:125], v[242:243]
	v_pk_add_f32 v[124:125], v[122:123], v[250:251]
	v_pk_add_f32 v[128:129], v[128:129], v[240:241]
	v_cvt_pk_bf16_f32 v122, v126, v127
	v_lshlrev_b32_e32 v252, 16, v244
	v_cvt_pk_bf16_f32 v123, v128, v129
	v_cvt_pk_bf16_f32 v124, v124, v125
	v_cvt_pk_bf16_f32 v125, v236, v237
	global_store_dwordx4 v[248:249], v[122:125], off
	v_lshlrev_b32_e32 v126, 16, v122
	v_lshlrev_b32_e32 v127, 16, v123
	v_and_b32_e32 v122, 0xffff0000, v122
	v_and_b32_e32 v123, 0xffff0000, v123
	v_lshlrev_b32_e32 v128, 16, v124
	v_and_b32_e32 v124, 0xffff0000, v124
	v_lshlrev_b32_e32 v129, 16, v125
	v_and_b32_e32 v125, 0xffff0000, v125
	v_mul_f32_e32 v122, v122, v122
	v_mul_f32_e32 v123, v123, v123
	v_mul_f32_e32 v124, v124, v124
	v_mul_f32_e32 v125, v125, v125
	v_fmac_f32_e32 v122, v126, v126
	v_fmac_f32_e32 v123, v127, v127
	v_fmac_f32_e32 v124, v128, v128
	v_fmac_f32_e32 v125, v129, v129
	v_add_f32_e32 v122, v122, v123
	v_add_f32_e32 v123, v124, v125
	v_and_b32_e32 v253, 0xffff0000, v244
	v_add_f32_e32 v128, v122, v123
	v_lshlrev_b32_e32 v122, 16, v245
	v_and_b32_e32 v123, 0xffff0000, v245
	v_lshlrev_b32_e32 v124, 16, v246
	v_and_b32_e32 v125, 0xffff0000, v246
	v_lshlrev_b32_e32 v126, 16, v247
	v_and_b32_e32 v127, 0xffff0000, v247
	v_pk_add_f32 v[120:121], v[120:121], v[122:123]
	v_pk_add_f32 v[118:119], v[118:119], v[252:253]
	v_pk_add_f32 v[122:123], v[116:117], v[126:127]
	v_pk_add_f32 v[116:117], v[114:115], v[124:125]
	v_cvt_pk_bf16_f32 v114, v118, v119
	v_cvt_pk_bf16_f32 v115, v120, v121
	s_nop 0
	v_cvt_pk_bf16_f32 v116, v116, v117
	v_cvt_pk_bf16_f32 v117, v122, v123
	global_store_dwordx4 v[248:249], v[114:117], off offset:256
	v_lshlrev_b32_e32 v118, 16, v114
	v_lshlrev_b32_e32 v119, 16, v115
	v_and_b32_e32 v114, 0xffff0000, v114
	v_and_b32_e32 v115, 0xffff0000, v115
	v_mul_f32_e32 v114, v114, v114
	v_mul_f32_e32 v115, v115, v115
	v_lshlrev_b32_e32 v120, 16, v116
	v_and_b32_e32 v116, 0xffff0000, v116
	v_lshlrev_b32_e32 v121, 16, v117
	v_and_b32_e32 v117, 0xffff0000, v117
	v_fmac_f32_e32 v114, v118, v118
	v_fmac_f32_e32 v115, v119, v119
	v_add_f32_e32 v114, v114, v115
	v_mul_f32_e32 v115, v116, v116
	v_mul_f32_e32 v116, v117, v117
	v_fmac_f32_e32 v115, v120, v120
	v_fmac_f32_e32 v116, v121, v121
	v_add_f32_e32 v115, v115, v116
	v_add_f32_e32 v114, v114, v115
	s_mov_b32 s2, 0
	v_add_f32_e32 v114, v128, v114
	v_mbcnt_lo_u32_b32 v115, -1, s2
	v_mbcnt_hi_u32_b32 v115, -1, v115
	v_lshlrev_b32_e32 v115, 2, v115
	v_xor_b32_e32 v115, 64, v115
	ds_bpermute_b32 v115, v115, v114
	s_mov_b32 s2, 0
	s_waitcnt lgkmcnt(0)
	v_add_f32_e32 v114, v114, v115
	v_mbcnt_lo_u32_b32 v115, -1, s2
	v_mbcnt_hi_u32_b32 v115, -1, v115
	v_lshlrev_b32_e32 v115, 2, v115
	v_xor_b32_e32 v115, 0x80, v115
	ds_bpermute_b32 v115, v115, v114
	s_and_saveexec_b64 s[22:23], s[4:5]
	s_cbranch_execz .LBB0_1105
	v_lshlrev_b64 v[116:117], 7, v[224:225]
	v_lshl_add_u64 v[116:117], s[10:11], 0, v[116:117]
	v_lshl_add_u64 v[116:117], s[20:21], 2, v[116:117]
	s_lshl_b32 s50, s37, 2
	v_lshl_add_u64 v[116:117], v[116:117], 0, s[50:51]
	s_waitcnt lgkmcnt(0)
	v_add_f32_e32 v114, v114, v115
	global_store_dword v[116:117], v114, off
